# Q phase: scale store flat->global, per-row waits count only the row loads (previous row stores stay in flight); plus F5 gate carry and K-loop trim
# speedup vs baseline: 1.0090x; 1.0090x over previous
.LBB0_541:
	s_andn2_b64 vcc, exec, s[4:5]
	s_cbranch_vccnz .LBB0_559
	s_add_u32 s10, s8, 0x44000000
	v_readlane_b32 s4, v254, 38
	s_addc_u32 s11, s9, 0
	s_add_i32 s6, s12, s4
	s_ashr_i32 s7, s6, 31
	s_lshl_b64 s[4:5], s[6:7], 12
	s_add_u32 s4, s10, s4
	s_addc_u32 s5, s11, s5
	v_lshlrev_b32_e32 v8, 6, v10
	global_load_dwordx4 v[4:7], v8, s[4:5]
	global_load_dwordx4 v[12:15], v8, s[4:5] offset:16
	global_load_dwordx4 v[16:19], v8, s[4:5] offset:32
	global_load_dwordx4 v[24:27], v8, s[4:5] offset:48
	v_and_b32_e32 v2, 64, v218
	v_lshlrev_b32_e32 v162, 5, v10
	v_xor_b32_e32 v11, 1, v218
	v_cmp_eq_u32_e64 s[4:5], 0, v10
	v_add_u32_e32 v10, 64, v2
	v_mov_b32_e32 v9, v163
	v_xor_b32_e32 v22, 2, v218
	v_cmp_lt_i32_e32 vcc, v11, v10
	v_lshl_add_u64 v[20:21], s[10:11], 0, v[8:9]
	v_xor_b32_e32 v23, 4, v218
	v_cndmask_b32_e32 v8, v218, v11, vcc
	v_cmp_lt_i32_e32 vcc, v22, v10
	v_lshl_add_u64 v[2:3], s[8:9], 0, v[162:163]
	s_mov_b64 s[10:11], 0x67000000
	v_cndmask_b32_e32 v9, v218, v22, vcc
	v_lshlrev_b32_e32 v22, 2, v8
	v_cmp_lt_i32_e32 vcc, v23, v10
	v_xor_b32_e32 v37, 8, v218
	v_xor_b32_e32 v38, 16, v218
	v_cndmask_b32_e32 v11, v218, v23, vcc
	v_lshlrev_b32_e32 v23, 2, v9
	v_cmp_lt_i32_e32 vcc, v37, v10
	v_xor_b32_e32 v39, 32, v218
	s_lshl_b64 s[12:13], s[6:7], 11
	s_lshl_b64 s[14:15], s[6:7], 2
	s_waitcnt vmcnt(0)
	v_cvt_f32_f16_e32 v40, v4
	v_cvt_f32_f16_sdwa v41, v4 dst_sel:DWORD dst_unused:UNUSED_PAD src0_sel:WORD_1
	v_cvt_f32_f16_e32 v42, v5
	v_cvt_f32_f16_sdwa v43, v5 dst_sel:DWORD dst_unused:UNUSED_PAD src0_sel:WORD_1
	v_cvt_f32_f16_e32 v44, v6
	v_cvt_f32_f16_sdwa v45, v6 dst_sel:DWORD dst_unused:UNUSED_PAD src0_sel:WORD_1
	v_cvt_f32_f16_e32 v46, v7
	v_cvt_f32_f16_sdwa v47, v7 dst_sel:DWORD dst_unused:UNUSED_PAD src0_sel:WORD_1
	v_cvt_f32_f16_e32 v48, v12
	v_cvt_f32_f16_sdwa v49, v12 dst_sel:DWORD dst_unused:UNUSED_PAD src0_sel:WORD_1
	v_max3_f32 v4, |v40|, 0, |v41|
	v_cvt_f32_f16_e32 v50, v13
	v_cvt_f32_f16_sdwa v51, v13 dst_sel:DWORD dst_unused:UNUSED_PAD src0_sel:WORD_1
	v_max3_f32 v4, v4, |v42|, |v43|
	v_cvt_f32_f16_e32 v52, v14
	v_cvt_f32_f16_sdwa v53, v14 dst_sel:DWORD dst_unused:UNUSED_PAD src0_sel:WORD_1
	v_max3_f32 v4, v4, |v44|, |v45|
	v_cvt_f32_f16_e32 v54, v15
	v_cvt_f32_f16_sdwa v55, v15 dst_sel:DWORD dst_unused:UNUSED_PAD src0_sel:WORD_1
	v_max3_f32 v4, v4, |v46|, |v47|
	v_cvt_f32_f16_e32 v56, v16
	v_cvt_f32_f16_sdwa v57, v16 dst_sel:DWORD dst_unused:UNUSED_PAD src0_sel:WORD_1
	v_max3_f32 v4, v4, |v48|, |v49|
	v_cvt_f32_f16_e32 v58, v17
	v_cvt_f32_f16_sdwa v59, v17 dst_sel:DWORD dst_unused:UNUSED_PAD src0_sel:WORD_1
	v_max3_f32 v4, v4, |v50|, |v51|
	v_cvt_f32_f16_e32 v60, v18
	v_cvt_f32_f16_sdwa v61, v18 dst_sel:DWORD dst_unused:UNUSED_PAD src0_sel:WORD_1
	v_max3_f32 v4, v4, |v52|, |v53|
	v_cvt_f32_f16_e32 v62, v19
	v_cvt_f32_f16_sdwa v36, v19 dst_sel:DWORD dst_unused:UNUSED_PAD src0_sel:WORD_1
	v_max3_f32 v4, v4, |v54|, |v55|
	v_cvt_f32_f16_e32 v35, v24
	v_cvt_f32_f16_sdwa v34, v24 dst_sel:DWORD dst_unused:UNUSED_PAD src0_sel:WORD_1
	v_max3_f32 v4, v4, |v56|, |v57|
	v_cvt_f32_f16_e32 v33, v25
	v_cvt_f32_f16_sdwa v32, v25 dst_sel:DWORD dst_unused:UNUSED_PAD src0_sel:WORD_1
	v_max3_f32 v4, v4, |v58|, |v59|
	v_cvt_f32_f16_e32 v31, v26
	v_cvt_f32_f16_sdwa v30, v26 dst_sel:DWORD dst_unused:UNUSED_PAD src0_sel:WORD_1
	v_max3_f32 v4, v4, |v60|, |v61|
	v_cvt_f32_f16_e32 v29, v27
	v_cvt_f32_f16_sdwa v28, v27 dst_sel:DWORD dst_unused:UNUSED_PAD src0_sel:WORD_1
	v_max3_f32 v4, v4, |v62|, |v36|
	v_max3_f32 v4, v4, |v35|, |v34|
	v_max3_f32 v4, v4, |v33|, |v32|
	v_max3_f32 v4, v4, |v31|, |v30|
	v_max3_f32 v4, v4, |v29|, |v28|
	ds_bpermute_b32 v5, v22, v4
	v_lshl_add_u64 v[18:19], v[2:3], 0, s[10:11]
	v_lshlrev_b32_e32 v24, 2, v11
	v_cndmask_b32_e32 v6, v218, v37, vcc
	v_lshlrev_b32_e32 v26, 2, v6
	s_waitcnt lgkmcnt(0)
	v_max_f32_e32 v5, v5, v5
	v_max_f32_e32 v4, v4, v5
	ds_bpermute_b32 v5, v23, v4
	v_cmp_lt_i32_e32 vcc, v38, v10
	s_add_i32 s10, s6, 0x100
	s_ashr_i32 s11, s10, 31
	v_cndmask_b32_e32 v7, v218, v38, vcc
	s_waitcnt lgkmcnt(0)
	v_max_f32_e32 v2, v5, v5
	v_max_f32_e32 v2, v4, v2
	ds_bpermute_b32 v3, v24, v2
	v_lshlrev_b32_e32 v27, 2, v7
	v_cmp_lt_i32_e32 vcc, v39, v10
	s_lshl_b64 s[16:17], s[10:11], 12
	s_add_u32 s7, s8, s14
	s_waitcnt lgkmcnt(0)
	v_max_f32_e32 v3, v3, v3
	v_max_f32_e32 v2, v2, v3
	ds_bpermute_b32 v3, v26, v2
	v_cndmask_b32_e32 v8, v218, v39, vcc
	v_lshlrev_b32_e32 v25, 2, v8
	s_addc_u32 s9, s9, s15
	s_add_u32 s8, s7, 0x6b000000
	s_waitcnt lgkmcnt(0)
	v_max_f32_e32 v3, v3, v3
	v_max_f32_e32 v4, v2, v3
	ds_bpermute_b32 v5, v27, v4
	v_lshl_add_u64 v[2:3], v[20:21], 0, s[16:17]
	global_load_dwordx4 v[14:17], v[2:3], off
	global_load_dwordx4 v[10:13], v[2:3], off offset:16
	s_addc_u32 s9, s9, 0
	s_waitcnt lgkmcnt(0)
	v_max_f32_e32 v5, v5, v5
	v_max_f32_e32 v37, v4, v5
	global_load_dwordx4 v[6:9], v[2:3], off offset:32
	s_nop 0
	global_load_dwordx4 v[2:5], v[2:3], off offset:48
	ds_bpermute_b32 v38, v25, v37
	s_waitcnt lgkmcnt(0)
	v_max_f32_e32 v38, v38, v38
	v_max_f32_e32 v37, v37, v38
	v_div_scale_f32 v38, s[14:15], v37, v37, s43
	v_rcp_f32_e32 v39, v38
	v_div_scale_f32 v63, vcc, s43, v37, s43
	v_fma_f32 v64, -v38, v39, 1.0
	v_fmac_f32_e32 v39, v64, v39
	v_mul_f32_e32 v64, v63, v39
	v_fma_f32 v65, -v38, v64, v63
	v_fmac_f32_e32 v64, v65, v39
	v_fma_f32 v38, -v38, v64, v63
	v_div_fmas_f32 v38, v38, v39, v64
	v_div_fixup_f32 v38, v38, v37, s43
	v_cmp_lt_f32_e32 vcc, 0, v37
	s_nop 1
	v_cndmask_b32_e32 v63, 0, v38, vcc
	v_mul_f32_e32 v39, v63, v41
	v_mul_f32_e32 v38, v63, v40
	v_mul_f32_e32 v40, v63, v42
	v_mul_f32_e32 v41, v63, v43
	v_mul_f32_e32 v43, v63, v45
	v_rndne_f32_e32 v39, v39
	v_mul_f32_e32 v42, v63, v44
	v_mul_f32_e32 v44, v63, v46
	v_mul_f32_e32 v45, v63, v47
	v_rndne_f32_e32 v38, v38
	v_rndne_f32_e32 v40, v40
	v_rndne_f32_e32 v41, v41
	v_rndne_f32_e32 v43, v43
	v_cvt_i32_f32_e32 v39, v39
	v_rndne_f32_e32 v42, v42
	v_rndne_f32_e32 v44, v44
	v_rndne_f32_e32 v45, v45
	v_cvt_i32_f32_e32 v38, v38
	v_cvt_i32_f32_sdwa v40, v40 dst_sel:WORD_1 dst_unused:UNUSED_PAD src0_sel:DWORD
	v_cvt_i32_f32_e32 v41, v41
	v_cvt_i32_f32_e32 v43, v43
	v_cvt_i32_f32_e32 v42, v42
	v_cvt_i32_f32_sdwa v44, v44 dst_sel:WORD_1 dst_unused:UNUSED_PAD src0_sel:DWORD
	v_cvt_i32_f32_e32 v45, v45
	v_lshlrev_b32_e32 v39, 8, v39
	v_and_b32_e32 v40, 0xff0000, v40
	v_perm_b32 v38, v41, v38, s68
	v_lshlrev_b32_e32 v41, 8, v43
	v_and_b32_e32 v39, 0xff00, v39
	v_and_b32_e32 v41, 0xff00, v41
	v_or3_b32 v38, v38, v39, v40
	v_and_b32_e32 v39, 0xff0000, v44
	v_perm_b32 v40, v45, v42, s68
	v_or3_b32 v39, v40, v41, v39
	v_mul_f32_e32 v41, v63, v49
	v_mul_f32_e32 v40, v63, v48
	v_rndne_f32_e32 v41, v41
	v_mul_f32_e32 v42, v63, v50
	v_mul_f32_e32 v43, v63, v51
	v_rndne_f32_e32 v40, v40
	v_cvt_i32_f32_e32 v41, v41
	v_rndne_f32_e32 v42, v42
	v_rndne_f32_e32 v43, v43
	v_cvt_i32_f32_e32 v40, v40
	v_cvt_i32_f32_sdwa v42, v42 dst_sel:WORD_1 dst_unused:UNUSED_PAD src0_sel:DWORD
	v_cvt_i32_f32_e32 v43, v43
	v_lshlrev_b32_e32 v41, 8, v41
	v_and_b32_e32 v41, 0xff00, v41
	v_and_b32_e32 v42, 0xff0000, v42
	v_perm_b32 v40, v43, v40, s68
	v_or3_b32 v40, v40, v41, v42
	v_mul_f32_e32 v42, v63, v53
	v_mul_f32_e32 v41, v63, v52
	v_rndne_f32_e32 v42, v42
	v_mul_f32_e32 v43, v63, v54
	v_mul_f32_e32 v44, v63, v55
	v_rndne_f32_e32 v41, v41
	v_cvt_i32_f32_e32 v42, v42
	v_rndne_f32_e32 v43, v43
	v_rndne_f32_e32 v44, v44
	v_cvt_i32_f32_e32 v41, v41
	v_cvt_i32_f32_sdwa v43, v43 dst_sel:WORD_1 dst_unused:UNUSED_PAD src0_sel:DWORD
	v_cvt_i32_f32_e32 v44, v44
	v_lshlrev_b32_e32 v42, 8, v42
	v_and_b32_e32 v42, 0xff00, v42
	v_and_b32_e32 v43, 0xff0000, v43
	v_perm_b32 v41, v44, v41, s68
	v_or3_b32 v41, v41, v42, v43
	v_mul_f32_e32 v43, v63, v57
	v_mul_f32_e32 v42, v63, v56
	v_rndne_f32_e32 v43, v43
	v_mul_f32_e32 v44, v63, v58
	v_mul_f32_e32 v45, v63, v59
	v_rndne_f32_e32 v42, v42
	v_cvt_i32_f32_e32 v43, v43
	v_rndne_f32_e32 v44, v44
	v_rndne_f32_e32 v45, v45
	v_cvt_i32_f32_e32 v42, v42
	v_cvt_i32_f32_sdwa v44, v44 dst_sel:WORD_1 dst_unused:UNUSED_PAD src0_sel:DWORD
	v_cvt_i32_f32_e32 v45, v45
	v_lshlrev_b32_e32 v43, 8, v43
	v_and_b32_e32 v43, 0xff00, v43
	v_and_b32_e32 v44, 0xff0000, v44
	v_perm_b32 v42, v45, v42, s68
	v_or3_b32 v42, v42, v43, v44
	v_mul_f32_e32 v44, v63, v61
	v_mul_f32_e32 v30, v63, v30
	v_mul_f32_e32 v43, v63, v60
	v_rndne_f32_e32 v44, v44
	v_mul_f32_e32 v45, v63, v62
	v_mul_f32_e32 v36, v63, v36
	v_mul_f32_e32 v34, v63, v34
	v_mul_f32_e32 v31, v63, v31
	v_rndne_f32_e32 v30, v30
	v_mul_f32_e32 v29, v63, v29
	v_mul_f32_e32 v28, v63, v28
	v_rndne_f32_e32 v43, v43
	v_cvt_i32_f32_e32 v44, v44
	v_rndne_f32_e32 v45, v45
	v_rndne_f32_e32 v36, v36
	v_mul_f32_e32 v35, v63, v35
	v_rndne_f32_e32 v34, v34
	v_mul_f32_e32 v33, v63, v33
	v_mul_f32_e32 v32, v63, v32
	v_rndne_f32_e32 v31, v31
	v_cvt_i32_f32_e32 v30, v30
	v_rndne_f32_e32 v29, v29
	v_rndne_f32_e32 v28, v28
	v_cvt_i32_f32_e32 v43, v43
	v_cvt_i32_f32_sdwa v45, v45 dst_sel:WORD_1 dst_unused:UNUSED_PAD src0_sel:DWORD
	v_cvt_i32_f32_e32 v36, v36
	v_rndne_f32_e32 v35, v35
	v_cvt_i32_f32_e32 v34, v34
	v_rndne_f32_e32 v33, v33
	v_rndne_f32_e32 v32, v32
	v_cvt_i32_f32_e32 v31, v31
	v_cvt_i32_f32_sdwa v29, v29 dst_sel:WORD_1 dst_unused:UNUSED_PAD src0_sel:DWORD
	v_cvt_i32_f32_e32 v28, v28
	v_cvt_i32_f32_e32 v35, v35
	v_cvt_i32_f32_sdwa v33, v33 dst_sel:WORD_1 dst_unused:UNUSED_PAD src0_sel:DWORD
	v_cvt_i32_f32_e32 v32, v32
	v_lshlrev_b32_e32 v44, 8, v44
	v_lshlrev_b32_e32 v30, 8, v30
	v_and_b32_e32 v44, 0xff00, v44
	v_and_b32_e32 v45, 0xff0000, v45
	v_perm_b32 v36, v36, v43, s68
	v_lshlrev_b32_e32 v34, 8, v34
	v_and_b32_e32 v30, 0xff00, v30
	v_and_b32_e32 v29, 0xff0000, v29
	v_perm_b32 v28, v28, v31, s68
	v_or3_b32 v43, v36, v44, v45
	v_and_b32_e32 v34, 0xff00, v34
	v_and_b32_e32 v33, 0xff0000, v33
	v_perm_b32 v32, v32, v35, s68
	v_or3_b32 v45, v28, v30, v29
	v_lshl_add_u64 v[28:29], v[18:19], 0, s[12:13]
	v_or3_b32 v44, v32, v34, v33
	global_store_dwordx4 v[28:29], v[38:41], off
	global_store_dwordx4 v[28:29], v[42:45], off offset:16
	s_and_saveexec_b64 s[12:13], s[4:5]
	s_cbranch_execz .LBB0_544
	v_mul_f32_e32 v30, 0x3c010204, v37
	v_mov_b64_e32 v[28:29], s[8:9]
	global_store_dword v[28:29], v30, off
.LBB0_544:
	s_or_b64 exec, exec, s[12:13]
	s_waitcnt vmcnt(2)
	v_cvt_f32_f16_e32 v29, v14
	v_cvt_f32_f16_sdwa v30, v14 dst_sel:DWORD dst_unused:UNUSED_PAD src0_sel:WORD_1
	v_cvt_f32_f16_e32 v31, v15
	v_cvt_f32_f16_sdwa v32, v15 dst_sel:DWORD dst_unused:UNUSED_PAD src0_sel:WORD_1
	v_cvt_f32_f16_e32 v33, v16
	v_cvt_f32_f16_sdwa v34, v16 dst_sel:DWORD dst_unused:UNUSED_PAD src0_sel:WORD_1
	v_cvt_f32_f16_e32 v35, v17
	v_cvt_f32_f16_sdwa v36, v17 dst_sel:DWORD dst_unused:UNUSED_PAD src0_sel:WORD_1
	v_max3_f32 v14, |v29|, 0, |v30|
	v_cvt_f32_f16_e32 v37, v10
	v_cvt_f32_f16_sdwa v38, v10 dst_sel:DWORD dst_unused:UNUSED_PAD src0_sel:WORD_1
	v_max3_f32 v14, v14, |v31|, |v32|
	v_cvt_f32_f16_e32 v39, v11
	v_cvt_f32_f16_sdwa v40, v11 dst_sel:DWORD dst_unused:UNUSED_PAD src0_sel:WORD_1
	v_max3_f32 v14, v14, |v33|, |v34|
	v_cvt_f32_f16_e32 v41, v12
	v_cvt_f32_f16_sdwa v42, v12 dst_sel:DWORD dst_unused:UNUSED_PAD src0_sel:WORD_1
	v_max3_f32 v14, v14, |v35|, |v36|
	v_cvt_f32_f16_e32 v43, v13
	v_cvt_f32_f16_sdwa v44, v13 dst_sel:DWORD dst_unused:UNUSED_PAD src0_sel:WORD_1
	v_max3_f32 v10, v14, |v37|, |v38|
	v_cvt_f32_f16_e32 v45, v6
	v_cvt_f32_f16_sdwa v46, v6 dst_sel:DWORD dst_unused:UNUSED_PAD src0_sel:WORD_1
	v_max3_f32 v10, v10, |v39|, |v40|
	v_cvt_f32_f16_e32 v47, v7
	v_cvt_f32_f16_sdwa v48, v7 dst_sel:DWORD dst_unused:UNUSED_PAD src0_sel:WORD_1
	v_max3_f32 v10, v10, |v41|, |v42|
	v_cvt_f32_f16_e32 v49, v8
	v_cvt_f32_f16_sdwa v50, v8 dst_sel:DWORD dst_unused:UNUSED_PAD src0_sel:WORD_1
	v_max3_f32 v10, v10, |v43|, |v44|
	v_cvt_f32_f16_e32 v51, v9
	v_cvt_f32_f16_sdwa v52, v9 dst_sel:DWORD dst_unused:UNUSED_PAD src0_sel:WORD_1
	v_max3_f32 v6, v10, |v45|, |v46|
	v_cvt_f32_f16_e32 v53, v2
	v_cvt_f32_f16_sdwa v54, v2 dst_sel:DWORD dst_unused:UNUSED_PAD src0_sel:WORD_1
	v_max3_f32 v6, v6, |v47|, |v48|
	v_cvt_f32_f16_e32 v55, v3
	v_cvt_f32_f16_sdwa v56, v3 dst_sel:DWORD dst_unused:UNUSED_PAD src0_sel:WORD_1
	v_max3_f32 v6, v6, |v49|, |v50|
	v_cvt_f32_f16_e32 v57, v4
	v_cvt_f32_f16_sdwa v58, v4 dst_sel:DWORD dst_unused:UNUSED_PAD src0_sel:WORD_1
	v_max3_f32 v6, v6, |v51|, |v52|
	v_cvt_f32_f16_e32 v59, v5
	v_cvt_f32_f16_sdwa v60, v5 dst_sel:DWORD dst_unused:UNUSED_PAD src0_sel:WORD_1
	v_max3_f32 v2, v6, |v53|, |v54|
	v_max3_f32 v2, v2, |v55|, |v56|
	v_max3_f32 v2, v2, |v57|, |v58|
	v_max3_f32 v2, v2, |v59|, |v60|
	ds_bpermute_b32 v3, v22, v2
	s_lshl_b64 s[12:13], s[10:11], 11
	s_add_i32 s10, s6, 0x200
	s_ashr_i32 s11, s10, 31
	s_lshl_b64 s[14:15], s[10:11], 12
	s_waitcnt lgkmcnt(0)
	v_max_f32_e32 v3, v3, v3
	v_max_f32_e32 v2, v2, v3
	ds_bpermute_b32 v3, v23, v2
	s_waitcnt lgkmcnt(0)
	v_max_f32_e32 v3, v3, v3
	v_max_f32_e32 v2, v2, v3
	ds_bpermute_b32 v3, v24, v2
	s_waitcnt lgkmcnt(0)
	v_max_f32_e32 v3, v3, v3
	v_max_f32_e32 v2, v2, v3
	ds_bpermute_b32 v3, v26, v2
	s_waitcnt lgkmcnt(0)
	v_max_f32_e32 v3, v3, v3
	v_max_f32_e32 v2, v2, v3
	ds_bpermute_b32 v3, v27, v2
	s_waitcnt lgkmcnt(0)
	v_max_f32_e32 v3, v3, v3
	v_max_f32_e32 v4, v2, v3
	ds_bpermute_b32 v5, v25, v4
	v_lshl_add_u64 v[2:3], v[20:21], 0, s[14:15]
	s_waitcnt lgkmcnt(0)
	v_max_f32_e32 v5, v5, v5
	v_max_f32_e32 v28, v4, v5
	global_load_dwordx4 v[14:17], v[2:3], off
	global_load_dwordx4 v[10:13], v[2:3], off offset:16
	global_load_dwordx4 v[6:9], v[2:3], off offset:32
	s_nop 0
	global_load_dwordx4 v[2:5], v[2:3], off offset:48
	v_div_scale_f32 v61, s[14:15], v28, v28, s43
	v_rcp_f32_e32 v62, v61
	s_nop 0
	v_fma_f32 v63, -v61, v62, 1.0
	v_fmac_f32_e32 v62, v63, v62
	v_div_scale_f32 v63, vcc, s43, v28, s43
	v_mul_f32_e32 v64, v63, v62
	v_fma_f32 v65, -v61, v64, v63
	v_fmac_f32_e32 v64, v65, v62
	v_fma_f32 v61, -v61, v64, v63
	v_div_fmas_f32 v61, v61, v62, v64
	v_div_fixup_f32 v61, v61, v28, s43
	v_cmp_lt_f32_e32 vcc, 0, v28
	s_nop 1
	v_cndmask_b32_e32 v61, 0, v61, vcc
	v_mul_f32_e32 v30, v61, v30
	v_mul_f32_e32 v29, v61, v29
	v_rndne_f32_e32 v30, v30
	v_mul_f32_e32 v31, v61, v31
	v_mul_f32_e32 v32, v61, v32
	v_rndne_f32_e32 v29, v29
	v_cvt_i32_f32_e32 v30, v30
	v_rndne_f32_e32 v31, v31
	v_rndne_f32_e32 v32, v32
	v_cvt_i32_f32_e32 v29, v29
	v_cvt_i32_f32_sdwa v31, v31 dst_sel:WORD_1 dst_unused:UNUSED_PAD src0_sel:DWORD
	v_cvt_i32_f32_e32 v32, v32
	v_lshlrev_b32_e32 v30, 8, v30
	v_and_b32_e32 v30, 0xff00, v30
	v_and_b32_e32 v31, 0xff0000, v31
	v_perm_b32 v29, v32, v29, s68
	v_or3_b32 v30, v29, v30, v31
	v_mul_f32_e32 v31, v61, v34
	v_mul_f32_e32 v29, v61, v33
	v_rndne_f32_e32 v31, v31
	v_mul_f32_e32 v32, v61, v35
	v_mul_f32_e32 v33, v61, v36
	v_rndne_f32_e32 v29, v29
	v_cvt_i32_f32_e32 v31, v31
	v_rndne_f32_e32 v32, v32
	v_rndne_f32_e32 v33, v33
	v_cvt_i32_f32_e32 v29, v29
	v_cvt_i32_f32_sdwa v32, v32 dst_sel:WORD_1 dst_unused:UNUSED_PAD src0_sel:DWORD
	v_cvt_i32_f32_e32 v33, v33
	v_lshlrev_b32_e32 v31, 8, v31
	v_and_b32_e32 v31, 0xff00, v31
	v_and_b32_e32 v32, 0xff0000, v32
	v_perm_b32 v29, v33, v29, s68
	v_or3_b32 v31, v29, v31, v32
	v_mul_f32_e32 v32, v61, v38
	v_mul_f32_e32 v29, v61, v37
	v_rndne_f32_e32 v32, v32
	v_mul_f32_e32 v33, v61, v39
	v_mul_f32_e32 v34, v61, v40
	v_rndne_f32_e32 v29, v29
	v_cvt_i32_f32_e32 v32, v32
	v_rndne_f32_e32 v33, v33
	v_rndne_f32_e32 v34, v34
	v_cvt_i32_f32_e32 v29, v29
	v_cvt_i32_f32_sdwa v33, v33 dst_sel:WORD_1 dst_unused:UNUSED_PAD src0_sel:DWORD
	v_cvt_i32_f32_e32 v34, v34
	v_lshlrev_b32_e32 v32, 8, v32
	v_and_b32_e32 v32, 0xff00, v32
	v_and_b32_e32 v33, 0xff0000, v33
	v_perm_b32 v29, v34, v29, s68
	v_or3_b32 v32, v29, v32, v33
	v_mul_f32_e32 v33, v61, v42
	v_mul_f32_e32 v29, v61, v41
	v_rndne_f32_e32 v33, v33
	v_mul_f32_e32 v34, v61, v43
	v_mul_f32_e32 v35, v61, v44
	v_rndne_f32_e32 v29, v29
	v_cvt_i32_f32_e32 v33, v33
	v_rndne_f32_e32 v34, v34
	v_rndne_f32_e32 v35, v35
	v_cvt_i32_f32_e32 v29, v29
	v_cvt_i32_f32_sdwa v34, v34 dst_sel:WORD_1 dst_unused:UNUSED_PAD src0_sel:DWORD
	v_cvt_i32_f32_e32 v35, v35
	v_lshlrev_b32_e32 v33, 8, v33
	v_and_b32_e32 v33, 0xff00, v33
	v_and_b32_e32 v34, 0xff0000, v34
	v_perm_b32 v29, v35, v29, s68
	v_or3_b32 v33, v29, v33, v34
	v_mul_f32_e32 v34, v61, v46
	v_mul_f32_e32 v29, v61, v45
	v_rndne_f32_e32 v34, v34
	v_mul_f32_e32 v35, v61, v47
	v_mul_f32_e32 v36, v61, v48
	v_rndne_f32_e32 v29, v29
	v_cvt_i32_f32_e32 v34, v34
	v_rndne_f32_e32 v35, v35
	v_rndne_f32_e32 v36, v36
	v_cvt_i32_f32_e32 v29, v29
	v_cvt_i32_f32_sdwa v35, v35 dst_sel:WORD_1 dst_unused:UNUSED_PAD src0_sel:DWORD
	v_cvt_i32_f32_e32 v36, v36
	v_lshlrev_b32_e32 v34, 8, v34
	v_and_b32_e32 v34, 0xff00, v34
	v_and_b32_e32 v35, 0xff0000, v35
	v_perm_b32 v29, v36, v29, s68
	v_or3_b32 v34, v29, v34, v35
	v_mul_f32_e32 v35, v61, v50
	v_mul_f32_e32 v29, v61, v49
	v_rndne_f32_e32 v35, v35
	v_mul_f32_e32 v36, v61, v51
	v_mul_f32_e32 v37, v61, v52
	v_rndne_f32_e32 v29, v29
	v_cvt_i32_f32_e32 v35, v35
	v_rndne_f32_e32 v36, v36
	v_rndne_f32_e32 v37, v37
	v_cvt_i32_f32_e32 v29, v29
	v_cvt_i32_f32_sdwa v36, v36 dst_sel:WORD_1 dst_unused:UNUSED_PAD src0_sel:DWORD
	v_cvt_i32_f32_e32 v37, v37
	v_lshlrev_b32_e32 v35, 8, v35
	v_and_b32_e32 v35, 0xff00, v35
	v_and_b32_e32 v36, 0xff0000, v36
	v_perm_b32 v29, v37, v29, s68
	v_or3_b32 v35, v29, v35, v36
	v_mul_f32_e32 v36, v61, v54
	v_mul_f32_e32 v29, v61, v53
	v_rndne_f32_e32 v36, v36
	v_mul_f32_e32 v37, v61, v55
	v_mul_f32_e32 v38, v61, v56
	v_rndne_f32_e32 v29, v29
	v_cvt_i32_f32_e32 v36, v36
	v_rndne_f32_e32 v37, v37
	v_rndne_f32_e32 v38, v38
	v_cvt_i32_f32_e32 v29, v29
	v_cvt_i32_f32_sdwa v37, v37 dst_sel:WORD_1 dst_unused:UNUSED_PAD src0_sel:DWORD
	v_cvt_i32_f32_e32 v38, v38
	v_lshlrev_b32_e32 v36, 8, v36
	v_and_b32_e32 v36, 0xff00, v36
	v_and_b32_e32 v37, 0xff0000, v37
	v_perm_b32 v29, v38, v29, s68
	v_or3_b32 v36, v29, v36, v37
	v_mul_f32_e32 v37, v61, v58
	v_mul_f32_e32 v29, v61, v57
	v_rndne_f32_e32 v37, v37
	v_mul_f32_e32 v38, v61, v59
	v_mul_f32_e32 v39, v61, v60
	v_rndne_f32_e32 v29, v29
	v_cvt_i32_f32_e32 v37, v37
	v_rndne_f32_e32 v38, v38
	v_rndne_f32_e32 v39, v39
	v_cvt_i32_f32_e32 v29, v29
	v_cvt_i32_f32_sdwa v38, v38 dst_sel:WORD_1 dst_unused:UNUSED_PAD src0_sel:DWORD
	v_cvt_i32_f32_e32 v39, v39
	v_lshlrev_b32_e32 v37, 8, v37
	v_and_b32_e32 v37, 0xff00, v37
	v_and_b32_e32 v38, 0xff0000, v38
	v_perm_b32 v29, v39, v29, s68
	v_or3_b32 v37, v29, v37, v38
	v_lshl_add_u64 v[38:39], v[18:19], 0, s[12:13]
	global_store_dwordx4 v[38:39], v[30:33], off
	global_store_dwordx4 v[38:39], v[34:37], off offset:16
	s_and_saveexec_b64 s[12:13], s[4:5]
	s_cbranch_execz .LBB0_546
	v_mul_f32_e32 v30, 0x3c010204, v28
	v_mov_b64_e32 v[28:29], s[8:9]
	global_store_dword v[28:29], v30, off offset:1024
.LBB0_546:
	s_or_b64 exec, exec, s[12:13]
	s_waitcnt vmcnt(2)
	v_cvt_f32_f16_e32 v29, v14
	v_cvt_f32_f16_sdwa v30, v14 dst_sel:DWORD dst_unused:UNUSED_PAD src0_sel:WORD_1
	v_cvt_f32_f16_e32 v31, v15
	v_cvt_f32_f16_sdwa v32, v15 dst_sel:DWORD dst_unused:UNUSED_PAD src0_sel:WORD_1
	v_cvt_f32_f16_e32 v33, v16
	v_cvt_f32_f16_sdwa v34, v16 dst_sel:DWORD dst_unused:UNUSED_PAD src0_sel:WORD_1
	v_cvt_f32_f16_e32 v35, v17
	v_cvt_f32_f16_sdwa v36, v17 dst_sel:DWORD dst_unused:UNUSED_PAD src0_sel:WORD_1
	v_max3_f32 v14, |v29|, 0, |v30|
	v_cvt_f32_f16_e32 v37, v10
	v_cvt_f32_f16_sdwa v38, v10 dst_sel:DWORD dst_unused:UNUSED_PAD src0_sel:WORD_1
	v_max3_f32 v14, v14, |v31|, |v32|
	v_cvt_f32_f16_e32 v39, v11
	v_cvt_f32_f16_sdwa v40, v11 dst_sel:DWORD dst_unused:UNUSED_PAD src0_sel:WORD_1
	v_max3_f32 v14, v14, |v33|, |v34|
	v_cvt_f32_f16_e32 v41, v12
	v_cvt_f32_f16_sdwa v42, v12 dst_sel:DWORD dst_unused:UNUSED_PAD src0_sel:WORD_1
	v_max3_f32 v14, v14, |v35|, |v36|
	v_cvt_f32_f16_e32 v43, v13
	v_cvt_f32_f16_sdwa v44, v13 dst_sel:DWORD dst_unused:UNUSED_PAD src0_sel:WORD_1
	v_max3_f32 v10, v14, |v37|, |v38|
	v_cvt_f32_f16_e32 v45, v6
	v_cvt_f32_f16_sdwa v46, v6 dst_sel:DWORD dst_unused:UNUSED_PAD src0_sel:WORD_1
	v_max3_f32 v10, v10, |v39|, |v40|
	v_cvt_f32_f16_e32 v47, v7
	v_cvt_f32_f16_sdwa v48, v7 dst_sel:DWORD dst_unused:UNUSED_PAD src0_sel:WORD_1
	v_max3_f32 v10, v10, |v41|, |v42|
	v_cvt_f32_f16_e32 v49, v8
	v_cvt_f32_f16_sdwa v50, v8 dst_sel:DWORD dst_unused:UNUSED_PAD src0_sel:WORD_1
	v_max3_f32 v10, v10, |v43|, |v44|
	v_cvt_f32_f16_e32 v51, v9
	v_cvt_f32_f16_sdwa v52, v9 dst_sel:DWORD dst_unused:UNUSED_PAD src0_sel:WORD_1
	v_max3_f32 v6, v10, |v45|, |v46|
	v_cvt_f32_f16_e32 v53, v2
	v_cvt_f32_f16_sdwa v54, v2 dst_sel:DWORD dst_unused:UNUSED_PAD src0_sel:WORD_1
	v_max3_f32 v6, v6, |v47|, |v48|
	v_cvt_f32_f16_e32 v55, v3
	v_cvt_f32_f16_sdwa v56, v3 dst_sel:DWORD dst_unused:UNUSED_PAD src0_sel:WORD_1
	v_max3_f32 v6, v6, |v49|, |v50|
	v_cvt_f32_f16_e32 v57, v4
	v_cvt_f32_f16_sdwa v58, v4 dst_sel:DWORD dst_unused:UNUSED_PAD src0_sel:WORD_1
	v_max3_f32 v6, v6, |v51|, |v52|
	v_cvt_f32_f16_e32 v59, v5
	v_cvt_f32_f16_sdwa v60, v5 dst_sel:DWORD dst_unused:UNUSED_PAD src0_sel:WORD_1
	v_max3_f32 v2, v6, |v53|, |v54|
	v_max3_f32 v2, v2, |v55|, |v56|
	v_max3_f32 v2, v2, |v57|, |v58|
	v_max3_f32 v2, v2, |v59|, |v60|
	ds_bpermute_b32 v3, v22, v2
	s_add_i32 s12, s6, 0x300
	s_ashr_i32 s13, s12, 31
	s_lshl_b64 s[14:15], s[12:13], 12
	s_lshl_b64 s[10:11], s[10:11], 11
	s_waitcnt lgkmcnt(0)
	v_max_f32_e32 v3, v3, v3
	v_max_f32_e32 v2, v2, v3
	ds_bpermute_b32 v3, v23, v2
	s_waitcnt lgkmcnt(0)
	v_max_f32_e32 v3, v3, v3
	v_max_f32_e32 v2, v2, v3
	ds_bpermute_b32 v3, v24, v2
	s_waitcnt lgkmcnt(0)
	v_max_f32_e32 v3, v3, v3
	v_max_f32_e32 v2, v2, v3
	ds_bpermute_b32 v3, v26, v2
	s_waitcnt lgkmcnt(0)
	v_max_f32_e32 v3, v3, v3
	v_max_f32_e32 v2, v2, v3
	ds_bpermute_b32 v3, v27, v2
	s_waitcnt lgkmcnt(0)
	v_max_f32_e32 v3, v3, v3
	v_max_f32_e32 v4, v2, v3
	ds_bpermute_b32 v5, v25, v4
	v_lshl_add_u64 v[2:3], v[20:21], 0, s[14:15]
	global_load_dwordx4 v[14:17], v[2:3], off
	global_load_dwordx4 v[10:13], v[2:3], off offset:16
	s_waitcnt lgkmcnt(0)
	v_max_f32_e32 v5, v5, v5
	v_max_f32_e32 v28, v4, v5
	global_load_dwordx4 v[6:9], v[2:3], off offset:32
	s_nop 0
	global_load_dwordx4 v[2:5], v[2:3], off offset:48
	v_div_scale_f32 v61, s[14:15], v28, v28, s43
	v_rcp_f32_e32 v62, v61
	s_nop 0
	v_fma_f32 v63, -v61, v62, 1.0
	v_fmac_f32_e32 v62, v63, v62
	v_div_scale_f32 v63, vcc, s43, v28, s43
	v_mul_f32_e32 v64, v63, v62
	v_fma_f32 v65, -v61, v64, v63
	v_fmac_f32_e32 v64, v65, v62
	v_fma_f32 v61, -v61, v64, v63
	v_div_fmas_f32 v61, v61, v62, v64
	v_div_fixup_f32 v61, v61, v28, s43
	v_cmp_lt_f32_e32 vcc, 0, v28
	s_nop 1
	v_cndmask_b32_e32 v61, 0, v61, vcc
	v_mul_f32_e32 v30, v61, v30
	v_mul_f32_e32 v29, v61, v29
	v_rndne_f32_e32 v30, v30
	v_mul_f32_e32 v31, v61, v31
	v_mul_f32_e32 v32, v61, v32
	v_rndne_f32_e32 v29, v29
	v_cvt_i32_f32_e32 v30, v30
	v_rndne_f32_e32 v31, v31
	v_rndne_f32_e32 v32, v32
	v_cvt_i32_f32_e32 v29, v29
	v_cvt_i32_f32_sdwa v31, v31 dst_sel:WORD_1 dst_unused:UNUSED_PAD src0_sel:DWORD
	v_cvt_i32_f32_e32 v32, v32
	v_lshlrev_b32_e32 v30, 8, v30
	v_and_b32_e32 v30, 0xff00, v30
	v_and_b32_e32 v31, 0xff0000, v31
	v_perm_b32 v29, v32, v29, s68
	v_or3_b32 v30, v29, v30, v31
	v_mul_f32_e32 v31, v61, v34
	v_mul_f32_e32 v29, v61, v33
	v_rndne_f32_e32 v31, v31
	v_mul_f32_e32 v32, v61, v35
	v_mul_f32_e32 v33, v61, v36
	v_rndne_f32_e32 v29, v29
	v_cvt_i32_f32_e32 v31, v31
	v_rndne_f32_e32 v32, v32
	v_rndne_f32_e32 v33, v33
	v_cvt_i32_f32_e32 v29, v29
	v_cvt_i32_f32_sdwa v32, v32 dst_sel:WORD_1 dst_unused:UNUSED_PAD src0_sel:DWORD
	v_cvt_i32_f32_e32 v33, v33
	v_lshlrev_b32_e32 v31, 8, v31
	v_and_b32_e32 v31, 0xff00, v31
	v_and_b32_e32 v32, 0xff0000, v32
	v_perm_b32 v29, v33, v29, s68
	v_or3_b32 v31, v29, v31, v32
	v_mul_f32_e32 v32, v61, v38
	v_mul_f32_e32 v29, v61, v37
	v_rndne_f32_e32 v32, v32
	v_mul_f32_e32 v33, v61, v39
	v_mul_f32_e32 v34, v61, v40
	v_rndne_f32_e32 v29, v29
	v_cvt_i32_f32_e32 v32, v32
	v_rndne_f32_e32 v33, v33
	v_rndne_f32_e32 v34, v34
	v_cvt_i32_f32_e32 v29, v29
	v_cvt_i32_f32_sdwa v33, v33 dst_sel:WORD_1 dst_unused:UNUSED_PAD src0_sel:DWORD
	v_cvt_i32_f32_e32 v34, v34
	v_lshlrev_b32_e32 v32, 8, v32
	v_and_b32_e32 v32, 0xff00, v32
	v_and_b32_e32 v33, 0xff0000, v33
	v_perm_b32 v29, v34, v29, s68
	v_or3_b32 v32, v29, v32, v33
	v_mul_f32_e32 v33, v61, v42
	v_mul_f32_e32 v29, v61, v41
	v_rndne_f32_e32 v33, v33
	v_mul_f32_e32 v34, v61, v43
	v_mul_f32_e32 v35, v61, v44
	v_rndne_f32_e32 v29, v29
	v_cvt_i32_f32_e32 v33, v33
	v_rndne_f32_e32 v34, v34
	v_rndne_f32_e32 v35, v35
	v_cvt_i32_f32_e32 v29, v29
	v_cvt_i32_f32_sdwa v34, v34 dst_sel:WORD_1 dst_unused:UNUSED_PAD src0_sel:DWORD
	v_cvt_i32_f32_e32 v35, v35
	v_lshlrev_b32_e32 v33, 8, v33
	v_and_b32_e32 v33, 0xff00, v33
	v_and_b32_e32 v34, 0xff0000, v34
	v_perm_b32 v29, v35, v29, s68
	v_or3_b32 v33, v29, v33, v34
	v_mul_f32_e32 v34, v61, v46
	v_mul_f32_e32 v29, v61, v45
	v_rndne_f32_e32 v34, v34
	v_mul_f32_e32 v35, v61, v47
	v_mul_f32_e32 v36, v61, v48
	v_rndne_f32_e32 v29, v29
	v_cvt_i32_f32_e32 v34, v34
	v_rndne_f32_e32 v35, v35
	v_rndne_f32_e32 v36, v36
	v_cvt_i32_f32_e32 v29, v29
	v_cvt_i32_f32_sdwa v35, v35 dst_sel:WORD_1 dst_unused:UNUSED_PAD src0_sel:DWORD
	v_cvt_i32_f32_e32 v36, v36
	v_lshlrev_b32_e32 v34, 8, v34
	v_and_b32_e32 v34, 0xff00, v34
	v_and_b32_e32 v35, 0xff0000, v35
	v_perm_b32 v29, v36, v29, s68
	v_or3_b32 v34, v29, v34, v35
	v_mul_f32_e32 v35, v61, v50
	v_mul_f32_e32 v29, v61, v49
	v_rndne_f32_e32 v35, v35
	v_mul_f32_e32 v36, v61, v51
	v_mul_f32_e32 v37, v61, v52
	v_rndne_f32_e32 v29, v29
	v_cvt_i32_f32_e32 v35, v35
	v_rndne_f32_e32 v36, v36
	v_rndne_f32_e32 v37, v37
	v_cvt_i32_f32_e32 v29, v29
	v_cvt_i32_f32_sdwa v36, v36 dst_sel:WORD_1 dst_unused:UNUSED_PAD src0_sel:DWORD
	v_cvt_i32_f32_e32 v37, v37
	v_lshlrev_b32_e32 v35, 8, v35
	v_and_b32_e32 v35, 0xff00, v35
	v_and_b32_e32 v36, 0xff0000, v36
	v_perm_b32 v29, v37, v29, s68
	v_or3_b32 v35, v29, v35, v36
	v_mul_f32_e32 v36, v61, v54
	v_mul_f32_e32 v29, v61, v53
	v_rndne_f32_e32 v36, v36
	v_mul_f32_e32 v37, v61, v55
	v_mul_f32_e32 v38, v61, v56
	v_rndne_f32_e32 v29, v29
	v_cvt_i32_f32_e32 v36, v36
	v_rndne_f32_e32 v37, v37
	v_rndne_f32_e32 v38, v38
	v_cvt_i32_f32_e32 v29, v29
	v_cvt_i32_f32_sdwa v37, v37 dst_sel:WORD_1 dst_unused:UNUSED_PAD src0_sel:DWORD
	v_cvt_i32_f32_e32 v38, v38
	v_lshlrev_b32_e32 v36, 8, v36
	v_and_b32_e32 v36, 0xff00, v36
	v_and_b32_e32 v37, 0xff0000, v37
	v_perm_b32 v29, v38, v29, s68
	v_or3_b32 v36, v29, v36, v37
	v_mul_f32_e32 v37, v61, v58
	v_mul_f32_e32 v29, v61, v57
	v_rndne_f32_e32 v37, v37
	v_mul_f32_e32 v38, v61, v59
	v_mul_f32_e32 v39, v61, v60
	v_rndne_f32_e32 v29, v29
	v_cvt_i32_f32_e32 v37, v37
	v_rndne_f32_e32 v38, v38
	v_rndne_f32_e32 v39, v39
	v_cvt_i32_f32_e32 v29, v29
	v_cvt_i32_f32_sdwa v38, v38 dst_sel:WORD_1 dst_unused:UNUSED_PAD src0_sel:DWORD
	v_cvt_i32_f32_e32 v39, v39
	v_lshlrev_b32_e32 v37, 8, v37
	v_and_b32_e32 v37, 0xff00, v37
	v_and_b32_e32 v38, 0xff0000, v38
	v_perm_b32 v29, v39, v29, s68
	v_or3_b32 v37, v29, v37, v38
	v_lshl_add_u64 v[38:39], v[18:19], 0, s[10:11]
	global_store_dwordx4 v[38:39], v[30:33], off
	global_store_dwordx4 v[38:39], v[34:37], off offset:16
	s_and_saveexec_b64 s[10:11], s[4:5]
	s_cbranch_execz .LBB0_548
	v_mul_f32_e32 v30, 0x3c010204, v28
	v_mov_b64_e32 v[28:29], s[8:9]
	global_store_dword v[28:29], v30, off offset:2048
.LBB0_548:
	s_or_b64 exec, exec, s[10:11]
	s_waitcnt vmcnt(2)
	v_cvt_f32_f16_e32 v29, v14
	v_cvt_f32_f16_sdwa v30, v14 dst_sel:DWORD dst_unused:UNUSED_PAD src0_sel:WORD_1
	v_cvt_f32_f16_e32 v31, v15
	v_cvt_f32_f16_sdwa v32, v15 dst_sel:DWORD dst_unused:UNUSED_PAD src0_sel:WORD_1
	v_cvt_f32_f16_e32 v33, v16
	v_cvt_f32_f16_sdwa v34, v16 dst_sel:DWORD dst_unused:UNUSED_PAD src0_sel:WORD_1
	v_cvt_f32_f16_e32 v35, v17
	v_cvt_f32_f16_sdwa v36, v17 dst_sel:DWORD dst_unused:UNUSED_PAD src0_sel:WORD_1
	v_max3_f32 v14, |v29|, 0, |v30|
	v_cvt_f32_f16_e32 v37, v10
	v_cvt_f32_f16_sdwa v38, v10 dst_sel:DWORD dst_unused:UNUSED_PAD src0_sel:WORD_1
	v_max3_f32 v14, v14, |v31|, |v32|
	v_cvt_f32_f16_e32 v39, v11
	v_cvt_f32_f16_sdwa v40, v11 dst_sel:DWORD dst_unused:UNUSED_PAD src0_sel:WORD_1
	v_max3_f32 v14, v14, |v33|, |v34|
	v_cvt_f32_f16_e32 v41, v12
	v_cvt_f32_f16_sdwa v42, v12 dst_sel:DWORD dst_unused:UNUSED_PAD src0_sel:WORD_1
	v_max3_f32 v14, v14, |v35|, |v36|
	v_cvt_f32_f16_e32 v43, v13
	v_cvt_f32_f16_sdwa v44, v13 dst_sel:DWORD dst_unused:UNUSED_PAD src0_sel:WORD_1
	v_max3_f32 v10, v14, |v37|, |v38|
	v_cvt_f32_f16_e32 v45, v6
	v_cvt_f32_f16_sdwa v46, v6 dst_sel:DWORD dst_unused:UNUSED_PAD src0_sel:WORD_1
	v_max3_f32 v10, v10, |v39|, |v40|
	v_cvt_f32_f16_e32 v47, v7
	v_cvt_f32_f16_sdwa v48, v7 dst_sel:DWORD dst_unused:UNUSED_PAD src0_sel:WORD_1
	v_max3_f32 v10, v10, |v41|, |v42|
	v_cvt_f32_f16_e32 v49, v8
	v_cvt_f32_f16_sdwa v50, v8 dst_sel:DWORD dst_unused:UNUSED_PAD src0_sel:WORD_1
	v_max3_f32 v10, v10, |v43|, |v44|
	v_cvt_f32_f16_e32 v51, v9
	v_cvt_f32_f16_sdwa v52, v9 dst_sel:DWORD dst_unused:UNUSED_PAD src0_sel:WORD_1
	v_max3_f32 v6, v10, |v45|, |v46|
	v_cvt_f32_f16_e32 v53, v2
	v_cvt_f32_f16_sdwa v54, v2 dst_sel:DWORD dst_unused:UNUSED_PAD src0_sel:WORD_1
	v_max3_f32 v6, v6, |v47|, |v48|
	v_cvt_f32_f16_e32 v55, v3
	v_cvt_f32_f16_sdwa v56, v3 dst_sel:DWORD dst_unused:UNUSED_PAD src0_sel:WORD_1
	v_max3_f32 v6, v6, |v49|, |v50|
	v_cvt_f32_f16_e32 v57, v4
	v_cvt_f32_f16_sdwa v58, v4 dst_sel:DWORD dst_unused:UNUSED_PAD src0_sel:WORD_1
	v_max3_f32 v6, v6, |v51|, |v52|
	v_cvt_f32_f16_e32 v59, v5
	v_cvt_f32_f16_sdwa v60, v5 dst_sel:DWORD dst_unused:UNUSED_PAD src0_sel:WORD_1
	v_max3_f32 v2, v6, |v53|, |v54|
	v_max3_f32 v2, v2, |v55|, |v56|
	v_max3_f32 v2, v2, |v57|, |v58|
	v_max3_f32 v2, v2, |v59|, |v60|
	ds_bpermute_b32 v3, v22, v2
	s_add_i32 s10, s6, 0x400
	s_ashr_i32 s11, s10, 31
	s_lshl_b64 s[14:15], s[10:11], 12
	s_lshl_b64 s[12:13], s[12:13], 11
	s_waitcnt lgkmcnt(0)
	v_max_f32_e32 v3, v3, v3
	v_max_f32_e32 v2, v2, v3
	ds_bpermute_b32 v3, v23, v2
	s_waitcnt lgkmcnt(0)
	v_max_f32_e32 v3, v3, v3
	v_max_f32_e32 v2, v2, v3
	ds_bpermute_b32 v3, v24, v2
	s_waitcnt lgkmcnt(0)
	v_max_f32_e32 v3, v3, v3
	v_max_f32_e32 v2, v2, v3
	ds_bpermute_b32 v3, v26, v2
	s_waitcnt lgkmcnt(0)
	v_max_f32_e32 v3, v3, v3
	v_max_f32_e32 v2, v2, v3
	ds_bpermute_b32 v3, v27, v2
	s_waitcnt lgkmcnt(0)
	v_max_f32_e32 v3, v3, v3
	v_max_f32_e32 v4, v2, v3
	ds_bpermute_b32 v5, v25, v4
	v_lshl_add_u64 v[2:3], v[20:21], 0, s[14:15]
	s_waitcnt lgkmcnt(0)
	v_max_f32_e32 v5, v5, v5
	v_max_f32_e32 v28, v4, v5
	global_load_dwordx4 v[14:17], v[2:3], off
	global_load_dwordx4 v[10:13], v[2:3], off offset:16
	global_load_dwordx4 v[6:9], v[2:3], off offset:32
	s_nop 0
	global_load_dwordx4 v[2:5], v[2:3], off offset:48
	v_div_scale_f32 v61, s[14:15], v28, v28, s43
	v_rcp_f32_e32 v62, v61
	s_nop 0
	v_fma_f32 v63, -v61, v62, 1.0
	v_fmac_f32_e32 v62, v63, v62
	v_div_scale_f32 v63, vcc, s43, v28, s43
	v_mul_f32_e32 v64, v63, v62
	v_fma_f32 v65, -v61, v64, v63
	v_fmac_f32_e32 v64, v65, v62
	v_fma_f32 v61, -v61, v64, v63
	v_div_fmas_f32 v61, v61, v62, v64
	v_div_fixup_f32 v61, v61, v28, s43
	v_cmp_lt_f32_e32 vcc, 0, v28
	s_nop 1
	v_cndmask_b32_e32 v61, 0, v61, vcc
	v_mul_f32_e32 v30, v61, v30
	v_mul_f32_e32 v29, v61, v29
	v_rndne_f32_e32 v30, v30
	v_mul_f32_e32 v31, v61, v31
	v_mul_f32_e32 v32, v61, v32
	v_rndne_f32_e32 v29, v29
	v_cvt_i32_f32_e32 v30, v30
	v_rndne_f32_e32 v31, v31
	v_rndne_f32_e32 v32, v32
	v_cvt_i32_f32_e32 v29, v29
	v_cvt_i32_f32_sdwa v31, v31 dst_sel:WORD_1 dst_unused:UNUSED_PAD src0_sel:DWORD
	v_cvt_i32_f32_e32 v32, v32
	v_lshlrev_b32_e32 v30, 8, v30
	v_and_b32_e32 v30, 0xff00, v30
	v_and_b32_e32 v31, 0xff0000, v31
	v_perm_b32 v29, v32, v29, s68
	v_or3_b32 v30, v29, v30, v31
	v_mul_f32_e32 v31, v61, v34
	v_mul_f32_e32 v29, v61, v33
	v_rndne_f32_e32 v31, v31
	v_mul_f32_e32 v32, v61, v35
	v_mul_f32_e32 v33, v61, v36
	v_rndne_f32_e32 v29, v29
	v_cvt_i32_f32_e32 v31, v31
	v_rndne_f32_e32 v32, v32
	v_rndne_f32_e32 v33, v33
	v_cvt_i32_f32_e32 v29, v29
	v_cvt_i32_f32_sdwa v32, v32 dst_sel:WORD_1 dst_unused:UNUSED_PAD src0_sel:DWORD
	v_cvt_i32_f32_e32 v33, v33
	v_lshlrev_b32_e32 v31, 8, v31
	v_and_b32_e32 v31, 0xff00, v31
	v_and_b32_e32 v32, 0xff0000, v32
	v_perm_b32 v29, v33, v29, s68
	v_or3_b32 v31, v29, v31, v32
	v_mul_f32_e32 v32, v61, v38
	v_mul_f32_e32 v29, v61, v37
	v_rndne_f32_e32 v32, v32
	v_mul_f32_e32 v33, v61, v39
	v_mul_f32_e32 v34, v61, v40
	v_rndne_f32_e32 v29, v29
	v_cvt_i32_f32_e32 v32, v32
	v_rndne_f32_e32 v33, v33
	v_rndne_f32_e32 v34, v34
	v_cvt_i32_f32_e32 v29, v29
	v_cvt_i32_f32_sdwa v33, v33 dst_sel:WORD_1 dst_unused:UNUSED_PAD src0_sel:DWORD
	v_cvt_i32_f32_e32 v34, v34
	v_lshlrev_b32_e32 v32, 8, v32
	v_and_b32_e32 v32, 0xff00, v32
	v_and_b32_e32 v33, 0xff0000, v33
	v_perm_b32 v29, v34, v29, s68
	v_or3_b32 v32, v29, v32, v33
	v_mul_f32_e32 v33, v61, v42
	v_mul_f32_e32 v29, v61, v41
	v_rndne_f32_e32 v33, v33
	v_mul_f32_e32 v34, v61, v43
	v_mul_f32_e32 v35, v61, v44
	v_rndne_f32_e32 v29, v29
	v_cvt_i32_f32_e32 v33, v33
	v_rndne_f32_e32 v34, v34
	v_rndne_f32_e32 v35, v35
	v_cvt_i32_f32_e32 v29, v29
	v_cvt_i32_f32_sdwa v34, v34 dst_sel:WORD_1 dst_unused:UNUSED_PAD src0_sel:DWORD
	v_cvt_i32_f32_e32 v35, v35
	v_lshlrev_b32_e32 v33, 8, v33
	v_and_b32_e32 v33, 0xff00, v33
	v_and_b32_e32 v34, 0xff0000, v34
	v_perm_b32 v29, v35, v29, s68
	v_or3_b32 v33, v29, v33, v34
	v_mul_f32_e32 v34, v61, v46
	v_mul_f32_e32 v29, v61, v45
	v_rndne_f32_e32 v34, v34
	v_mul_f32_e32 v35, v61, v47
	v_mul_f32_e32 v36, v61, v48
	v_rndne_f32_e32 v29, v29
	v_cvt_i32_f32_e32 v34, v34
	v_rndne_f32_e32 v35, v35
	v_rndne_f32_e32 v36, v36
	v_cvt_i32_f32_e32 v29, v29
	v_cvt_i32_f32_sdwa v35, v35 dst_sel:WORD_1 dst_unused:UNUSED_PAD src0_sel:DWORD
	v_cvt_i32_f32_e32 v36, v36
	v_lshlrev_b32_e32 v34, 8, v34
	v_and_b32_e32 v34, 0xff00, v34
	v_and_b32_e32 v35, 0xff0000, v35
	v_perm_b32 v29, v36, v29, s68
	v_or3_b32 v34, v29, v34, v35
	v_mul_f32_e32 v35, v61, v50
	v_mul_f32_e32 v29, v61, v49
	v_rndne_f32_e32 v35, v35
	v_mul_f32_e32 v36, v61, v51
	v_mul_f32_e32 v37, v61, v52
	v_rndne_f32_e32 v29, v29
	v_cvt_i32_f32_e32 v35, v35
	v_rndne_f32_e32 v36, v36
	v_rndne_f32_e32 v37, v37
	v_cvt_i32_f32_e32 v29, v29
	v_cvt_i32_f32_sdwa v36, v36 dst_sel:WORD_1 dst_unused:UNUSED_PAD src0_sel:DWORD
	v_cvt_i32_f32_e32 v37, v37
	v_lshlrev_b32_e32 v35, 8, v35
	v_and_b32_e32 v35, 0xff00, v35
	v_and_b32_e32 v36, 0xff0000, v36
	v_perm_b32 v29, v37, v29, s68
	v_or3_b32 v35, v29, v35, v36
	v_mul_f32_e32 v36, v61, v54
	v_mul_f32_e32 v29, v61, v53
	v_rndne_f32_e32 v36, v36
	v_mul_f32_e32 v37, v61, v55
	v_mul_f32_e32 v38, v61, v56
	v_rndne_f32_e32 v29, v29
	v_cvt_i32_f32_e32 v36, v36
	v_rndne_f32_e32 v37, v37
	v_rndne_f32_e32 v38, v38
	v_cvt_i32_f32_e32 v29, v29
	v_cvt_i32_f32_sdwa v37, v37 dst_sel:WORD_1 dst_unused:UNUSED_PAD src0_sel:DWORD
	v_cvt_i32_f32_e32 v38, v38
	v_lshlrev_b32_e32 v36, 8, v36
	v_and_b32_e32 v36, 0xff00, v36
	v_and_b32_e32 v37, 0xff0000, v37
	v_perm_b32 v29, v38, v29, s68
	v_or3_b32 v36, v29, v36, v37
	v_mul_f32_e32 v37, v61, v58
	v_mul_f32_e32 v29, v61, v57
	v_rndne_f32_e32 v37, v37
	v_mul_f32_e32 v38, v61, v59
	v_mul_f32_e32 v39, v61, v60
	v_rndne_f32_e32 v29, v29
	v_cvt_i32_f32_e32 v37, v37
	v_rndne_f32_e32 v38, v38
	v_rndne_f32_e32 v39, v39
	v_cvt_i32_f32_e32 v29, v29
	v_cvt_i32_f32_sdwa v38, v38 dst_sel:WORD_1 dst_unused:UNUSED_PAD src0_sel:DWORD
	v_cvt_i32_f32_e32 v39, v39
	v_lshlrev_b32_e32 v37, 8, v37
	v_and_b32_e32 v37, 0xff00, v37
	v_and_b32_e32 v38, 0xff0000, v38
	v_perm_b32 v29, v39, v29, s68
	v_or3_b32 v37, v29, v37, v38
	v_lshl_add_u64 v[38:39], v[18:19], 0, s[12:13]
	global_store_dwordx4 v[38:39], v[30:33], off
	global_store_dwordx4 v[38:39], v[34:37], off offset:16
	s_and_saveexec_b64 s[12:13], s[4:5]
	s_cbranch_execz .LBB0_550
	v_mul_f32_e32 v30, 0x3c010204, v28
	v_mov_b64_e32 v[28:29], s[8:9]
	global_store_dword v[28:29], v30, off offset:3072
.LBB0_550:
	s_or_b64 exec, exec, s[12:13]
	s_waitcnt vmcnt(2)
	v_cvt_f32_f16_e32 v29, v14
	v_cvt_f32_f16_sdwa v30, v14 dst_sel:DWORD dst_unused:UNUSED_PAD src0_sel:WORD_1
	v_cvt_f32_f16_e32 v31, v15
	v_cvt_f32_f16_sdwa v32, v15 dst_sel:DWORD dst_unused:UNUSED_PAD src0_sel:WORD_1
	v_cvt_f32_f16_e32 v33, v16
	v_cvt_f32_f16_sdwa v34, v16 dst_sel:DWORD dst_unused:UNUSED_PAD src0_sel:WORD_1
	v_cvt_f32_f16_e32 v35, v17
	v_cvt_f32_f16_sdwa v36, v17 dst_sel:DWORD dst_unused:UNUSED_PAD src0_sel:WORD_1
	v_max3_f32 v14, |v29|, 0, |v30|
	v_cvt_f32_f16_e32 v37, v10
	v_cvt_f32_f16_sdwa v38, v10 dst_sel:DWORD dst_unused:UNUSED_PAD src0_sel:WORD_1
	v_max3_f32 v14, v14, |v31|, |v32|
	v_cvt_f32_f16_e32 v39, v11
	v_cvt_f32_f16_sdwa v40, v11 dst_sel:DWORD dst_unused:UNUSED_PAD src0_sel:WORD_1
	v_max3_f32 v14, v14, |v33|, |v34|
	v_cvt_f32_f16_e32 v41, v12
	v_cvt_f32_f16_sdwa v42, v12 dst_sel:DWORD dst_unused:UNUSED_PAD src0_sel:WORD_1
	v_max3_f32 v14, v14, |v35|, |v36|
	v_cvt_f32_f16_e32 v43, v13
	v_cvt_f32_f16_sdwa v44, v13 dst_sel:DWORD dst_unused:UNUSED_PAD src0_sel:WORD_1
	v_max3_f32 v10, v14, |v37|, |v38|
	v_cvt_f32_f16_e32 v45, v6
	v_cvt_f32_f16_sdwa v46, v6 dst_sel:DWORD dst_unused:UNUSED_PAD src0_sel:WORD_1
	v_max3_f32 v10, v10, |v39|, |v40|
	v_cvt_f32_f16_e32 v47, v7
	v_cvt_f32_f16_sdwa v48, v7 dst_sel:DWORD dst_unused:UNUSED_PAD src0_sel:WORD_1
	v_max3_f32 v10, v10, |v41|, |v42|
	v_cvt_f32_f16_e32 v49, v8
	v_cvt_f32_f16_sdwa v50, v8 dst_sel:DWORD dst_unused:UNUSED_PAD src0_sel:WORD_1
	v_max3_f32 v10, v10, |v43|, |v44|
	v_cvt_f32_f16_e32 v51, v9
	v_cvt_f32_f16_sdwa v52, v9 dst_sel:DWORD dst_unused:UNUSED_PAD src0_sel:WORD_1
	v_max3_f32 v6, v10, |v45|, |v46|
	v_cvt_f32_f16_e32 v53, v2
	v_cvt_f32_f16_sdwa v54, v2 dst_sel:DWORD dst_unused:UNUSED_PAD src0_sel:WORD_1
	v_max3_f32 v6, v6, |v47|, |v48|
	v_cvt_f32_f16_e32 v55, v3
	v_cvt_f32_f16_sdwa v56, v3 dst_sel:DWORD dst_unused:UNUSED_PAD src0_sel:WORD_1
	v_max3_f32 v6, v6, |v49|, |v50|
	v_cvt_f32_f16_e32 v57, v4
	v_cvt_f32_f16_sdwa v58, v4 dst_sel:DWORD dst_unused:UNUSED_PAD src0_sel:WORD_1
	v_max3_f32 v6, v6, |v51|, |v52|
	v_cvt_f32_f16_e32 v59, v5
	v_cvt_f32_f16_sdwa v60, v5 dst_sel:DWORD dst_unused:UNUSED_PAD src0_sel:WORD_1
	v_max3_f32 v2, v6, |v53|, |v54|
	v_max3_f32 v2, v2, |v55|, |v56|
	v_max3_f32 v2, v2, |v57|, |v58|
	v_max3_f32 v2, v2, |v59|, |v60|
	ds_bpermute_b32 v3, v22, v2
	s_add_i32 s12, s6, 0x500
	s_ashr_i32 s13, s12, 31
	s_lshl_b64 s[14:15], s[12:13], 12
	s_waitcnt lgkmcnt(0)
	v_max_f32_e32 v3, v3, v3
	v_max_f32_e32 v2, v2, v3
	ds_bpermute_b32 v3, v23, v2
	s_waitcnt lgkmcnt(0)
	v_max_f32_e32 v3, v3, v3
	v_max_f32_e32 v2, v2, v3
	ds_bpermute_b32 v3, v24, v2
	s_waitcnt lgkmcnt(0)
	v_max_f32_e32 v3, v3, v3
	v_max_f32_e32 v2, v2, v3
	ds_bpermute_b32 v3, v26, v2
	s_waitcnt lgkmcnt(0)
	v_max_f32_e32 v3, v3, v3
	v_max_f32_e32 v4, v2, v3
	ds_bpermute_b32 v5, v27, v4
	v_lshl_add_u64 v[2:3], v[20:21], 0, s[14:15]
	s_waitcnt lgkmcnt(0)
	v_max_f32_e32 v5, v5, v5
	v_max_f32_e32 v28, v4, v5
	ds_bpermute_b32 v61, v25, v28
	global_load_dwordx4 v[14:17], v[2:3], off
	global_load_dwordx4 v[10:13], v[2:3], off offset:16
	global_load_dwordx4 v[6:9], v[2:3], off offset:32
	s_nop 0
	global_load_dwordx4 v[2:5], v[2:3], off offset:48
	s_waitcnt lgkmcnt(0)
	v_max_f32_e32 v61, v61, v61
	v_max_f32_e32 v28, v28, v61
	v_div_scale_f32 v61, s[14:15], v28, v28, s43
	v_rcp_f32_e32 v62, v61
	s_lshl_b64 s[14:15], s[10:11], 11
	s_add_u32 s10, s8, 0x1000
	s_addc_u32 s11, s9, 0
	v_fma_f32 v63, -v61, v62, 1.0
	v_fmac_f32_e32 v62, v63, v62
	v_div_scale_f32 v63, vcc, s43, v28, s43
	v_mul_f32_e32 v64, v63, v62
	v_fma_f32 v65, -v61, v64, v63
	v_fmac_f32_e32 v64, v65, v62
	v_fma_f32 v61, -v61, v64, v63
	v_div_fmas_f32 v61, v61, v62, v64
	v_div_fixup_f32 v61, v61, v28, s43
	v_cmp_lt_f32_e32 vcc, 0, v28
	s_nop 1
	v_cndmask_b32_e32 v61, 0, v61, vcc
	v_mul_f32_e32 v30, v61, v30
	v_mul_f32_e32 v29, v61, v29
	v_rndne_f32_e32 v30, v30
	v_mul_f32_e32 v31, v61, v31
	v_mul_f32_e32 v32, v61, v32
	v_rndne_f32_e32 v29, v29
	v_cvt_i32_f32_e32 v30, v30
	v_rndne_f32_e32 v31, v31
	v_rndne_f32_e32 v32, v32
	v_cvt_i32_f32_e32 v29, v29
	v_cvt_i32_f32_sdwa v31, v31 dst_sel:WORD_1 dst_unused:UNUSED_PAD src0_sel:DWORD
	v_cvt_i32_f32_e32 v32, v32
	v_lshlrev_b32_e32 v30, 8, v30
	v_and_b32_e32 v30, 0xff00, v30
	v_and_b32_e32 v31, 0xff0000, v31
	v_perm_b32 v29, v32, v29, s68
	v_or3_b32 v30, v29, v30, v31
	v_mul_f32_e32 v31, v61, v34
	v_mul_f32_e32 v29, v61, v33
	v_rndne_f32_e32 v31, v31
	v_mul_f32_e32 v32, v61, v35
	v_mul_f32_e32 v33, v61, v36
	v_rndne_f32_e32 v29, v29
	v_cvt_i32_f32_e32 v31, v31
	v_rndne_f32_e32 v32, v32
	v_rndne_f32_e32 v33, v33
	v_cvt_i32_f32_e32 v29, v29
	v_cvt_i32_f32_sdwa v32, v32 dst_sel:WORD_1 dst_unused:UNUSED_PAD src0_sel:DWORD
	v_cvt_i32_f32_e32 v33, v33
	v_lshlrev_b32_e32 v31, 8, v31
	v_and_b32_e32 v31, 0xff00, v31
	v_and_b32_e32 v32, 0xff0000, v32
	v_perm_b32 v29, v33, v29, s68
	v_or3_b32 v31, v29, v31, v32
	v_mul_f32_e32 v32, v61, v38
	v_mul_f32_e32 v29, v61, v37
	v_rndne_f32_e32 v32, v32
	v_mul_f32_e32 v33, v61, v39
	v_mul_f32_e32 v34, v61, v40
	v_rndne_f32_e32 v29, v29
	v_cvt_i32_f32_e32 v32, v32
	v_rndne_f32_e32 v33, v33
	v_rndne_f32_e32 v34, v34
	v_cvt_i32_f32_e32 v29, v29
	v_cvt_i32_f32_sdwa v33, v33 dst_sel:WORD_1 dst_unused:UNUSED_PAD src0_sel:DWORD
	v_cvt_i32_f32_e32 v34, v34
	v_lshlrev_b32_e32 v32, 8, v32
	v_and_b32_e32 v32, 0xff00, v32
	v_and_b32_e32 v33, 0xff0000, v33
	v_perm_b32 v29, v34, v29, s68
	v_or3_b32 v32, v29, v32, v33
	v_mul_f32_e32 v33, v61, v42
	v_mul_f32_e32 v29, v61, v41
	v_rndne_f32_e32 v33, v33
	v_mul_f32_e32 v34, v61, v43
	v_mul_f32_e32 v35, v61, v44
	v_rndne_f32_e32 v29, v29
	v_cvt_i32_f32_e32 v33, v33
	v_rndne_f32_e32 v34, v34
	v_rndne_f32_e32 v35, v35
	v_cvt_i32_f32_e32 v29, v29
	v_cvt_i32_f32_sdwa v34, v34 dst_sel:WORD_1 dst_unused:UNUSED_PAD src0_sel:DWORD
	v_cvt_i32_f32_e32 v35, v35
	v_lshlrev_b32_e32 v33, 8, v33
	v_and_b32_e32 v33, 0xff00, v33
	v_and_b32_e32 v34, 0xff0000, v34
	v_perm_b32 v29, v35, v29, s68
	v_or3_b32 v33, v29, v33, v34
	v_mul_f32_e32 v34, v61, v46
	v_mul_f32_e32 v29, v61, v45
	v_rndne_f32_e32 v34, v34
	v_mul_f32_e32 v35, v61, v47
	v_mul_f32_e32 v36, v61, v48
	v_rndne_f32_e32 v29, v29
	v_cvt_i32_f32_e32 v34, v34
	v_rndne_f32_e32 v35, v35
	v_rndne_f32_e32 v36, v36
	v_cvt_i32_f32_e32 v29, v29
	v_cvt_i32_f32_sdwa v35, v35 dst_sel:WORD_1 dst_unused:UNUSED_PAD src0_sel:DWORD
	v_cvt_i32_f32_e32 v36, v36
	v_lshlrev_b32_e32 v34, 8, v34
	v_and_b32_e32 v34, 0xff00, v34
	v_and_b32_e32 v35, 0xff0000, v35
	v_perm_b32 v29, v36, v29, s68
	v_or3_b32 v34, v29, v34, v35
	v_mul_f32_e32 v35, v61, v50
	v_mul_f32_e32 v29, v61, v49
	v_rndne_f32_e32 v35, v35
	v_mul_f32_e32 v36, v61, v51
	v_mul_f32_e32 v37, v61, v52
	v_rndne_f32_e32 v29, v29
	v_cvt_i32_f32_e32 v35, v35
	v_rndne_f32_e32 v36, v36
	v_rndne_f32_e32 v37, v37
	v_cvt_i32_f32_e32 v29, v29
	v_cvt_i32_f32_sdwa v36, v36 dst_sel:WORD_1 dst_unused:UNUSED_PAD src0_sel:DWORD
	v_cvt_i32_f32_e32 v37, v37
	v_lshlrev_b32_e32 v35, 8, v35
	v_and_b32_e32 v35, 0xff00, v35
	v_and_b32_e32 v36, 0xff0000, v36
	v_perm_b32 v29, v37, v29, s68
	v_or3_b32 v35, v29, v35, v36
	v_mul_f32_e32 v36, v61, v54
	v_mul_f32_e32 v29, v61, v53
	v_rndne_f32_e32 v36, v36
	v_mul_f32_e32 v37, v61, v55
	v_mul_f32_e32 v38, v61, v56
	v_rndne_f32_e32 v29, v29
	v_cvt_i32_f32_e32 v36, v36
	v_rndne_f32_e32 v37, v37
	v_rndne_f32_e32 v38, v38
	v_cvt_i32_f32_e32 v29, v29
	v_cvt_i32_f32_sdwa v37, v37 dst_sel:WORD_1 dst_unused:UNUSED_PAD src0_sel:DWORD
	v_cvt_i32_f32_e32 v38, v38
	v_lshlrev_b32_e32 v36, 8, v36
	v_and_b32_e32 v36, 0xff00, v36
	v_and_b32_e32 v37, 0xff0000, v37
	v_perm_b32 v29, v38, v29, s68
	v_or3_b32 v36, v29, v36, v37
	v_mul_f32_e32 v37, v61, v58
	v_mul_f32_e32 v29, v61, v57
	v_rndne_f32_e32 v37, v37
	v_mul_f32_e32 v38, v61, v59
	v_mul_f32_e32 v39, v61, v60
	v_rndne_f32_e32 v29, v29
	v_cvt_i32_f32_e32 v37, v37
	v_rndne_f32_e32 v38, v38
	v_rndne_f32_e32 v39, v39
	v_cvt_i32_f32_e32 v29, v29
	v_cvt_i32_f32_sdwa v38, v38 dst_sel:WORD_1 dst_unused:UNUSED_PAD src0_sel:DWORD
	v_cvt_i32_f32_e32 v39, v39
	v_lshlrev_b32_e32 v37, 8, v37
	v_and_b32_e32 v37, 0xff00, v37
	v_and_b32_e32 v38, 0xff0000, v38
	v_perm_b32 v29, v39, v29, s68
	v_or3_b32 v37, v29, v37, v38
	v_lshl_add_u64 v[38:39], v[18:19], 0, s[14:15]
	global_store_dwordx4 v[38:39], v[30:33], off
	global_store_dwordx4 v[38:39], v[34:37], off offset:16
	s_and_saveexec_b64 s[14:15], s[4:5]
	s_cbranch_execz .LBB0_552
	v_mul_f32_e32 v30, 0x3c010204, v28
	v_mov_b64_e32 v[28:29], s[10:11]
	global_store_dword v[28:29], v30, off
.LBB0_552:
	s_or_b64 exec, exec, s[14:15]
	s_waitcnt vmcnt(2)
	v_cvt_f32_f16_e32 v29, v14
	v_cvt_f32_f16_sdwa v30, v14 dst_sel:DWORD dst_unused:UNUSED_PAD src0_sel:WORD_1
	v_cvt_f32_f16_e32 v31, v15
	v_cvt_f32_f16_sdwa v32, v15 dst_sel:DWORD dst_unused:UNUSED_PAD src0_sel:WORD_1
	v_cvt_f32_f16_e32 v33, v16
	v_cvt_f32_f16_sdwa v34, v16 dst_sel:DWORD dst_unused:UNUSED_PAD src0_sel:WORD_1
	v_cvt_f32_f16_e32 v35, v17
	v_cvt_f32_f16_sdwa v36, v17 dst_sel:DWORD dst_unused:UNUSED_PAD src0_sel:WORD_1
	v_max3_f32 v14, |v29|, 0, |v30|
	v_cvt_f32_f16_e32 v37, v10
	v_cvt_f32_f16_sdwa v38, v10 dst_sel:DWORD dst_unused:UNUSED_PAD src0_sel:WORD_1
	v_max3_f32 v14, v14, |v31|, |v32|
	v_cvt_f32_f16_e32 v39, v11
	v_cvt_f32_f16_sdwa v40, v11 dst_sel:DWORD dst_unused:UNUSED_PAD src0_sel:WORD_1
	v_max3_f32 v14, v14, |v33|, |v34|
	v_cvt_f32_f16_e32 v41, v12
	v_cvt_f32_f16_sdwa v42, v12 dst_sel:DWORD dst_unused:UNUSED_PAD src0_sel:WORD_1
	v_max3_f32 v14, v14, |v35|, |v36|
	v_cvt_f32_f16_e32 v43, v13
	v_cvt_f32_f16_sdwa v44, v13 dst_sel:DWORD dst_unused:UNUSED_PAD src0_sel:WORD_1
	v_max3_f32 v10, v14, |v37|, |v38|
	v_cvt_f32_f16_e32 v45, v6
	v_cvt_f32_f16_sdwa v46, v6 dst_sel:DWORD dst_unused:UNUSED_PAD src0_sel:WORD_1
	v_max3_f32 v10, v10, |v39|, |v40|
	v_cvt_f32_f16_e32 v47, v7
	v_cvt_f32_f16_sdwa v48, v7 dst_sel:DWORD dst_unused:UNUSED_PAD src0_sel:WORD_1
	v_max3_f32 v10, v10, |v41|, |v42|
	v_cvt_f32_f16_e32 v49, v8
	v_cvt_f32_f16_sdwa v50, v8 dst_sel:DWORD dst_unused:UNUSED_PAD src0_sel:WORD_1
	v_max3_f32 v10, v10, |v43|, |v44|
	v_cvt_f32_f16_e32 v51, v9
	v_cvt_f32_f16_sdwa v52, v9 dst_sel:DWORD dst_unused:UNUSED_PAD src0_sel:WORD_1
	v_max3_f32 v6, v10, |v45|, |v46|
	v_cvt_f32_f16_e32 v53, v2
	v_cvt_f32_f16_sdwa v54, v2 dst_sel:DWORD dst_unused:UNUSED_PAD src0_sel:WORD_1
	v_max3_f32 v6, v6, |v47|, |v48|
	v_cvt_f32_f16_e32 v55, v3
	v_cvt_f32_f16_sdwa v56, v3 dst_sel:DWORD dst_unused:UNUSED_PAD src0_sel:WORD_1
	v_max3_f32 v6, v6, |v49|, |v50|
	v_cvt_f32_f16_e32 v57, v4
	v_cvt_f32_f16_sdwa v58, v4 dst_sel:DWORD dst_unused:UNUSED_PAD src0_sel:WORD_1
	v_max3_f32 v6, v6, |v51|, |v52|
	v_cvt_f32_f16_e32 v59, v5
	v_cvt_f32_f16_sdwa v60, v5 dst_sel:DWORD dst_unused:UNUSED_PAD src0_sel:WORD_1
	v_max3_f32 v2, v6, |v53|, |v54|
	v_max3_f32 v2, v2, |v55|, |v56|
	v_max3_f32 v2, v2, |v57|, |v58|
	v_max3_f32 v2, v2, |v59|, |v60|
	ds_bpermute_b32 v3, v22, v2
	s_lshl_b64 s[14:15], s[12:13], 11
	s_add_i32 s12, s6, 0x600
	s_ashr_i32 s13, s12, 31
	s_lshl_b64 s[16:17], s[12:13], 12
	s_waitcnt lgkmcnt(0)
	v_max_f32_e32 v3, v3, v3
	v_max_f32_e32 v2, v2, v3
	ds_bpermute_b32 v3, v23, v2
	s_waitcnt lgkmcnt(0)
	v_max_f32_e32 v3, v3, v3
	v_max_f32_e32 v2, v2, v3
	ds_bpermute_b32 v3, v24, v2
	s_waitcnt lgkmcnt(0)
	v_max_f32_e32 v3, v3, v3
	v_max_f32_e32 v2, v2, v3
	ds_bpermute_b32 v3, v26, v2
	s_waitcnt lgkmcnt(0)
	v_max_f32_e32 v3, v3, v3
	v_max_f32_e32 v2, v2, v3
	ds_bpermute_b32 v3, v27, v2
	s_waitcnt lgkmcnt(0)
	v_max_f32_e32 v3, v3, v3
	v_max_f32_e32 v4, v2, v3
	ds_bpermute_b32 v5, v25, v4
	v_lshl_add_u64 v[2:3], v[20:21], 0, s[16:17]
	s_waitcnt lgkmcnt(0)
	v_max_f32_e32 v5, v5, v5
	v_max_f32_e32 v28, v4, v5
	global_load_dwordx4 v[14:17], v[2:3], off
	global_load_dwordx4 v[10:13], v[2:3], off offset:16
	global_load_dwordx4 v[6:9], v[2:3], off offset:32
	s_nop 0
	global_load_dwordx4 v[2:5], v[2:3], off offset:48
	v_div_scale_f32 v61, s[16:17], v28, v28, s43
	v_rcp_f32_e32 v62, v61
	s_nop 0
	v_fma_f32 v63, -v61, v62, 1.0
	v_fmac_f32_e32 v62, v63, v62
	v_div_scale_f32 v63, vcc, s43, v28, s43
	v_mul_f32_e32 v64, v63, v62
	v_fma_f32 v65, -v61, v64, v63
	v_fmac_f32_e32 v64, v65, v62
	v_fma_f32 v61, -v61, v64, v63
	v_div_fmas_f32 v61, v61, v62, v64
	v_div_fixup_f32 v61, v61, v28, s43
	v_cmp_lt_f32_e32 vcc, 0, v28
	s_nop 1
	v_cndmask_b32_e32 v61, 0, v61, vcc
	v_mul_f32_e32 v30, v61, v30
	v_mul_f32_e32 v29, v61, v29
	v_rndne_f32_e32 v30, v30
	v_mul_f32_e32 v31, v61, v31
	v_mul_f32_e32 v32, v61, v32
	v_rndne_f32_e32 v29, v29
	v_cvt_i32_f32_e32 v30, v30
	v_rndne_f32_e32 v31, v31
	v_rndne_f32_e32 v32, v32
	v_cvt_i32_f32_e32 v29, v29
	v_cvt_i32_f32_sdwa v31, v31 dst_sel:WORD_1 dst_unused:UNUSED_PAD src0_sel:DWORD
	v_cvt_i32_f32_e32 v32, v32
	v_lshlrev_b32_e32 v30, 8, v30
	v_and_b32_e32 v30, 0xff00, v30
	v_and_b32_e32 v31, 0xff0000, v31
	v_perm_b32 v29, v32, v29, s68
	v_or3_b32 v30, v29, v30, v31
	v_mul_f32_e32 v31, v61, v34
	v_mul_f32_e32 v29, v61, v33
	v_rndne_f32_e32 v31, v31
	v_mul_f32_e32 v32, v61, v35
	v_mul_f32_e32 v33, v61, v36
	v_rndne_f32_e32 v29, v29
	v_cvt_i32_f32_e32 v31, v31
	v_rndne_f32_e32 v32, v32
	v_rndne_f32_e32 v33, v33
	v_cvt_i32_f32_e32 v29, v29
	v_cvt_i32_f32_sdwa v32, v32 dst_sel:WORD_1 dst_unused:UNUSED_PAD src0_sel:DWORD
	v_cvt_i32_f32_e32 v33, v33
	v_lshlrev_b32_e32 v31, 8, v31
	v_and_b32_e32 v31, 0xff00, v31
	v_and_b32_e32 v32, 0xff0000, v32
	v_perm_b32 v29, v33, v29, s68
	v_or3_b32 v31, v29, v31, v32
	v_mul_f32_e32 v32, v61, v38
	v_mul_f32_e32 v29, v61, v37
	v_rndne_f32_e32 v32, v32
	v_mul_f32_e32 v33, v61, v39
	v_mul_f32_e32 v34, v61, v40
	v_rndne_f32_e32 v29, v29
	v_cvt_i32_f32_e32 v32, v32
	v_rndne_f32_e32 v33, v33
	v_rndne_f32_e32 v34, v34
	v_cvt_i32_f32_e32 v29, v29
	v_cvt_i32_f32_sdwa v33, v33 dst_sel:WORD_1 dst_unused:UNUSED_PAD src0_sel:DWORD
	v_cvt_i32_f32_e32 v34, v34
	v_lshlrev_b32_e32 v32, 8, v32
	v_and_b32_e32 v32, 0xff00, v32
	v_and_b32_e32 v33, 0xff0000, v33
	v_perm_b32 v29, v34, v29, s68
	v_or3_b32 v32, v29, v32, v33
	v_mul_f32_e32 v33, v61, v42
	v_mul_f32_e32 v29, v61, v41
	v_rndne_f32_e32 v33, v33
	v_mul_f32_e32 v34, v61, v43
	v_mul_f32_e32 v35, v61, v44
	v_rndne_f32_e32 v29, v29
	v_cvt_i32_f32_e32 v33, v33
	v_rndne_f32_e32 v34, v34
	v_rndne_f32_e32 v35, v35
	v_cvt_i32_f32_e32 v29, v29
	v_cvt_i32_f32_sdwa v34, v34 dst_sel:WORD_1 dst_unused:UNUSED_PAD src0_sel:DWORD
	v_cvt_i32_f32_e32 v35, v35
	v_lshlrev_b32_e32 v33, 8, v33
	v_and_b32_e32 v33, 0xff00, v33
	v_and_b32_e32 v34, 0xff0000, v34
	v_perm_b32 v29, v35, v29, s68
	v_or3_b32 v33, v29, v33, v34
	v_mul_f32_e32 v34, v61, v46
	v_mul_f32_e32 v29, v61, v45
	v_rndne_f32_e32 v34, v34
	v_mul_f32_e32 v35, v61, v47
	v_mul_f32_e32 v36, v61, v48
	v_rndne_f32_e32 v29, v29
	v_cvt_i32_f32_e32 v34, v34
	v_rndne_f32_e32 v35, v35
	v_rndne_f32_e32 v36, v36
	v_cvt_i32_f32_e32 v29, v29
	v_cvt_i32_f32_sdwa v35, v35 dst_sel:WORD_1 dst_unused:UNUSED_PAD src0_sel:DWORD
	v_cvt_i32_f32_e32 v36, v36
	v_lshlrev_b32_e32 v34, 8, v34
	v_and_b32_e32 v34, 0xff00, v34
	v_and_b32_e32 v35, 0xff0000, v35
	v_perm_b32 v29, v36, v29, s68
	v_or3_b32 v34, v29, v34, v35
	v_mul_f32_e32 v35, v61, v50
	v_mul_f32_e32 v29, v61, v49
	v_rndne_f32_e32 v35, v35
	v_mul_f32_e32 v36, v61, v51
	v_mul_f32_e32 v37, v61, v52
	v_rndne_f32_e32 v29, v29
	v_cvt_i32_f32_e32 v35, v35
	v_rndne_f32_e32 v36, v36
	v_rndne_f32_e32 v37, v37
	v_cvt_i32_f32_e32 v29, v29
	v_cvt_i32_f32_sdwa v36, v36 dst_sel:WORD_1 dst_unused:UNUSED_PAD src0_sel:DWORD
	v_cvt_i32_f32_e32 v37, v37
	v_lshlrev_b32_e32 v35, 8, v35
	v_and_b32_e32 v35, 0xff00, v35
	v_and_b32_e32 v36, 0xff0000, v36
	v_perm_b32 v29, v37, v29, s68
	v_or3_b32 v35, v29, v35, v36
	v_mul_f32_e32 v36, v61, v54
	v_mul_f32_e32 v29, v61, v53
	v_rndne_f32_e32 v36, v36
	v_mul_f32_e32 v37, v61, v55
	v_mul_f32_e32 v38, v61, v56
	v_rndne_f32_e32 v29, v29
	v_cvt_i32_f32_e32 v36, v36
	v_rndne_f32_e32 v37, v37
	v_rndne_f32_e32 v38, v38
	v_cvt_i32_f32_e32 v29, v29
	v_cvt_i32_f32_sdwa v37, v37 dst_sel:WORD_1 dst_unused:UNUSED_PAD src0_sel:DWORD
	v_cvt_i32_f32_e32 v38, v38
	v_lshlrev_b32_e32 v36, 8, v36
	v_and_b32_e32 v36, 0xff00, v36
	v_and_b32_e32 v37, 0xff0000, v37
	v_perm_b32 v29, v38, v29, s68
	v_or3_b32 v36, v29, v36, v37
	v_mul_f32_e32 v37, v61, v58
	v_mul_f32_e32 v29, v61, v57
	v_rndne_f32_e32 v37, v37
	v_mul_f32_e32 v38, v61, v59
	v_mul_f32_e32 v39, v61, v60
	v_rndne_f32_e32 v29, v29
	v_cvt_i32_f32_e32 v37, v37
	v_rndne_f32_e32 v38, v38
	v_rndne_f32_e32 v39, v39
	v_cvt_i32_f32_e32 v29, v29
	v_cvt_i32_f32_sdwa v38, v38 dst_sel:WORD_1 dst_unused:UNUSED_PAD src0_sel:DWORD
	v_cvt_i32_f32_e32 v39, v39
	v_lshlrev_b32_e32 v37, 8, v37
	v_and_b32_e32 v37, 0xff00, v37
	v_and_b32_e32 v38, 0xff0000, v38
	v_perm_b32 v29, v39, v29, s68
	v_or3_b32 v37, v29, v37, v38
	v_lshl_add_u64 v[38:39], v[18:19], 0, s[14:15]
	global_store_dwordx4 v[38:39], v[30:33], off
	global_store_dwordx4 v[38:39], v[34:37], off offset:16
	s_and_saveexec_b64 s[14:15], s[4:5]
	s_cbranch_execz .LBB0_554
	v_mul_f32_e32 v30, 0x3c010204, v28
	v_mov_b64_e32 v[28:29], s[10:11]
	global_store_dword v[28:29], v30, off offset:1024
.LBB0_554:
	s_or_b64 exec, exec, s[14:15]
	s_waitcnt vmcnt(2)
	v_cvt_f32_f16_e32 v28, v14
	v_cvt_f32_f16_sdwa v29, v14 dst_sel:DWORD dst_unused:UNUSED_PAD src0_sel:WORD_1
	v_cvt_f32_f16_e32 v30, v15
	v_cvt_f32_f16_sdwa v31, v15 dst_sel:DWORD dst_unused:UNUSED_PAD src0_sel:WORD_1
	v_cvt_f32_f16_e32 v32, v16
	v_cvt_f32_f16_sdwa v33, v16 dst_sel:DWORD dst_unused:UNUSED_PAD src0_sel:WORD_1
	v_cvt_f32_f16_e32 v34, v17
	v_cvt_f32_f16_sdwa v35, v17 dst_sel:DWORD dst_unused:UNUSED_PAD src0_sel:WORD_1
	v_max3_f32 v14, |v28|, 0, |v29|
	v_cvt_f32_f16_e32 v36, v10
	v_cvt_f32_f16_sdwa v37, v10 dst_sel:DWORD dst_unused:UNUSED_PAD src0_sel:WORD_1
	v_max3_f32 v14, v14, |v30|, |v31|
	v_cvt_f32_f16_e32 v38, v11
	v_cvt_f32_f16_sdwa v39, v11 dst_sel:DWORD dst_unused:UNUSED_PAD src0_sel:WORD_1
	v_max3_f32 v14, v14, |v32|, |v33|
	v_cvt_f32_f16_e32 v40, v12
	v_cvt_f32_f16_sdwa v41, v12 dst_sel:DWORD dst_unused:UNUSED_PAD src0_sel:WORD_1
	v_max3_f32 v14, v14, |v34|, |v35|
	v_cvt_f32_f16_e32 v42, v13
	v_cvt_f32_f16_sdwa v43, v13 dst_sel:DWORD dst_unused:UNUSED_PAD src0_sel:WORD_1
	v_max3_f32 v10, v14, |v36|, |v37|
	v_cvt_f32_f16_e32 v44, v6
	v_cvt_f32_f16_sdwa v45, v6 dst_sel:DWORD dst_unused:UNUSED_PAD src0_sel:WORD_1
	v_max3_f32 v10, v10, |v38|, |v39|
	v_cvt_f32_f16_e32 v46, v7
	v_cvt_f32_f16_sdwa v47, v7 dst_sel:DWORD dst_unused:UNUSED_PAD src0_sel:WORD_1
	v_max3_f32 v10, v10, |v40|, |v41|
	v_cvt_f32_f16_e32 v48, v8
	v_cvt_f32_f16_sdwa v49, v8 dst_sel:DWORD dst_unused:UNUSED_PAD src0_sel:WORD_1
	v_max3_f32 v10, v10, |v42|, |v43|
	v_cvt_f32_f16_e32 v50, v9
	v_cvt_f32_f16_sdwa v51, v9 dst_sel:DWORD dst_unused:UNUSED_PAD src0_sel:WORD_1
	v_max3_f32 v6, v10, |v44|, |v45|
	v_cvt_f32_f16_e32 v52, v2
	v_cvt_f32_f16_sdwa v53, v2 dst_sel:DWORD dst_unused:UNUSED_PAD src0_sel:WORD_1
	v_max3_f32 v6, v6, |v46|, |v47|
	v_cvt_f32_f16_e32 v54, v3
	v_cvt_f32_f16_sdwa v55, v3 dst_sel:DWORD dst_unused:UNUSED_PAD src0_sel:WORD_1
	v_max3_f32 v6, v6, |v48|, |v49|
	v_cvt_f32_f16_e32 v56, v4
	v_cvt_f32_f16_sdwa v57, v4 dst_sel:DWORD dst_unused:UNUSED_PAD src0_sel:WORD_1
	v_max3_f32 v6, v6, |v50|, |v51|
	v_cvt_f32_f16_e32 v58, v5
	v_cvt_f32_f16_sdwa v59, v5 dst_sel:DWORD dst_unused:UNUSED_PAD src0_sel:WORD_1
	v_max3_f32 v2, v6, |v52|, |v53|
	v_max3_f32 v2, v2, |v54|, |v55|
	v_max3_f32 v2, v2, |v56|, |v57|
	v_max3_f32 v2, v2, |v58|, |v59|
	ds_bpermute_b32 v3, v22, v2
	s_add_i32 s10, s6, 0x700
	s_ashr_i32 s11, s10, 31
	s_lshl_b64 s[6:7], s[10:11], 12
	s_lshl_b64 s[12:13], s[12:13], 11
	s_waitcnt lgkmcnt(0)
	v_max_f32_e32 v3, v3, v3
	v_max_f32_e32 v2, v2, v3
	ds_bpermute_b32 v3, v23, v2
	s_waitcnt lgkmcnt(0)
	v_max_f32_e32 v3, v3, v3
	v_max_f32_e32 v2, v2, v3
	ds_bpermute_b32 v3, v24, v2
	s_waitcnt lgkmcnt(0)
	v_max_f32_e32 v3, v3, v3
	v_max_f32_e32 v2, v2, v3
	ds_bpermute_b32 v3, v26, v2
	s_waitcnt lgkmcnt(0)
	v_max_f32_e32 v3, v3, v3
	v_max_f32_e32 v4, v2, v3
	ds_bpermute_b32 v5, v27, v4
	v_lshl_add_u64 v[2:3], v[20:21], 0, s[6:7]
	s_waitcnt lgkmcnt(0)
	v_max_f32_e32 v5, v5, v5
	v_max_f32_e32 v20, v4, v5
	ds_bpermute_b32 v21, v25, v20
	global_load_dwordx4 v[14:17], v[2:3], off
	global_load_dwordx4 v[10:13], v[2:3], off offset:16
	global_load_dwordx4 v[6:9], v[2:3], off offset:32
	s_nop 0
	global_load_dwordx4 v[2:5], v[2:3], off offset:48
	s_waitcnt lgkmcnt(0)
	v_max_f32_e32 v21, v21, v21
	v_max_f32_e32 v20, v20, v21
	v_div_scale_f32 v21, s[6:7], v20, v20, s43
	v_rcp_f32_e32 v60, v21
	s_add_u32 s6, s8, 0x1800
	s_addc_u32 s7, s9, 0
	v_fma_f32 v61, -v21, v60, 1.0
	v_fmac_f32_e32 v60, v61, v60
	v_div_scale_f32 v61, vcc, s43, v20, s43
	v_mul_f32_e32 v62, v61, v60
	v_fma_f32 v63, -v21, v62, v61
	v_fmac_f32_e32 v62, v63, v60
	v_fma_f32 v21, -v21, v62, v61
	v_div_fmas_f32 v21, v21, v60, v62
	v_div_fixup_f32 v21, v21, v20, s43
	v_cmp_lt_f32_e32 vcc, 0, v20
	s_nop 1
	v_cndmask_b32_e32 v21, 0, v21, vcc
	v_mul_f32_e32 v29, v21, v29
	v_mul_f32_e32 v28, v21, v28
	v_rndne_f32_e32 v29, v29
	v_mul_f32_e32 v30, v21, v30
	v_mul_f32_e32 v31, v21, v31
	v_rndne_f32_e32 v28, v28
	v_cvt_i32_f32_e32 v29, v29
	v_rndne_f32_e32 v30, v30
	v_rndne_f32_e32 v31, v31
	v_cvt_i32_f32_e32 v28, v28
	v_cvt_i32_f32_sdwa v30, v30 dst_sel:WORD_1 dst_unused:UNUSED_PAD src0_sel:DWORD
	v_cvt_i32_f32_e32 v31, v31
	v_lshlrev_b32_e32 v29, 8, v29
	v_and_b32_e32 v29, 0xff00, v29
	v_and_b32_e32 v30, 0xff0000, v30
	v_perm_b32 v28, v31, v28, s68
	v_or3_b32 v28, v28, v29, v30
	v_mul_f32_e32 v30, v21, v33
	v_mul_f32_e32 v29, v21, v32
	v_rndne_f32_e32 v30, v30
	v_mul_f32_e32 v31, v21, v34
	v_mul_f32_e32 v32, v21, v35
	v_rndne_f32_e32 v29, v29
	v_cvt_i32_f32_e32 v30, v30
	v_rndne_f32_e32 v31, v31
	v_rndne_f32_e32 v32, v32
	v_cvt_i32_f32_e32 v29, v29
	v_cvt_i32_f32_sdwa v31, v31 dst_sel:WORD_1 dst_unused:UNUSED_PAD src0_sel:DWORD
	v_cvt_i32_f32_e32 v32, v32
	v_lshlrev_b32_e32 v30, 8, v30
	v_and_b32_e32 v30, 0xff00, v30
	v_and_b32_e32 v31, 0xff0000, v31
	v_perm_b32 v29, v32, v29, s68
	v_or3_b32 v29, v29, v30, v31
	v_mul_f32_e32 v31, v21, v37
	v_mul_f32_e32 v30, v21, v36
	v_rndne_f32_e32 v31, v31
	v_mul_f32_e32 v32, v21, v38
	v_mul_f32_e32 v33, v21, v39
	v_rndne_f32_e32 v30, v30
	v_cvt_i32_f32_e32 v31, v31
	v_rndne_f32_e32 v32, v32
	v_rndne_f32_e32 v33, v33
	v_cvt_i32_f32_e32 v30, v30
	v_cvt_i32_f32_sdwa v32, v32 dst_sel:WORD_1 dst_unused:UNUSED_PAD src0_sel:DWORD
	v_cvt_i32_f32_e32 v33, v33
	v_lshlrev_b32_e32 v31, 8, v31
	v_and_b32_e32 v31, 0xff00, v31
	v_and_b32_e32 v32, 0xff0000, v32
	v_perm_b32 v30, v33, v30, s68
	v_or3_b32 v30, v30, v31, v32
	v_mul_f32_e32 v32, v21, v41
	v_mul_f32_e32 v31, v21, v40
	v_rndne_f32_e32 v32, v32
	v_mul_f32_e32 v33, v21, v42
	v_mul_f32_e32 v34, v21, v43
	v_rndne_f32_e32 v31, v31
	v_cvt_i32_f32_e32 v32, v32
	v_rndne_f32_e32 v33, v33
	v_rndne_f32_e32 v34, v34
	v_cvt_i32_f32_e32 v31, v31
	v_cvt_i32_f32_sdwa v33, v33 dst_sel:WORD_1 dst_unused:UNUSED_PAD src0_sel:DWORD
	v_cvt_i32_f32_e32 v34, v34
	v_lshlrev_b32_e32 v32, 8, v32
	v_and_b32_e32 v32, 0xff00, v32
	v_and_b32_e32 v33, 0xff0000, v33
	v_perm_b32 v31, v34, v31, s68
	v_or3_b32 v31, v31, v32, v33
	v_mul_f32_e32 v33, v21, v45
	v_mul_f32_e32 v32, v21, v44
	v_rndne_f32_e32 v33, v33
	v_mul_f32_e32 v34, v21, v46
	v_mul_f32_e32 v35, v21, v47
	v_rndne_f32_e32 v32, v32
	v_cvt_i32_f32_e32 v33, v33
	v_rndne_f32_e32 v34, v34
	v_rndne_f32_e32 v35, v35
	v_cvt_i32_f32_e32 v32, v32
	v_cvt_i32_f32_sdwa v34, v34 dst_sel:WORD_1 dst_unused:UNUSED_PAD src0_sel:DWORD
	v_cvt_i32_f32_e32 v35, v35
	v_lshlrev_b32_e32 v33, 8, v33
	v_and_b32_e32 v33, 0xff00, v33
	v_and_b32_e32 v34, 0xff0000, v34
	v_perm_b32 v32, v35, v32, s68
	v_or3_b32 v32, v32, v33, v34
	v_mul_f32_e32 v34, v21, v49
	v_mul_f32_e32 v33, v21, v48
	v_rndne_f32_e32 v34, v34
	v_mul_f32_e32 v35, v21, v50
	v_mul_f32_e32 v36, v21, v51
	v_rndne_f32_e32 v33, v33
	v_cvt_i32_f32_e32 v34, v34
	v_rndne_f32_e32 v35, v35
	v_rndne_f32_e32 v36, v36
	v_cvt_i32_f32_e32 v33, v33
	v_cvt_i32_f32_sdwa v35, v35 dst_sel:WORD_1 dst_unused:UNUSED_PAD src0_sel:DWORD
	v_cvt_i32_f32_e32 v36, v36
	v_lshlrev_b32_e32 v34, 8, v34
	v_and_b32_e32 v34, 0xff00, v34
	v_and_b32_e32 v35, 0xff0000, v35
	v_perm_b32 v33, v36, v33, s68
	v_or3_b32 v33, v33, v34, v35
	v_mul_f32_e32 v35, v21, v53
	v_mul_f32_e32 v34, v21, v52
	v_rndne_f32_e32 v35, v35
	v_mul_f32_e32 v36, v21, v54
	v_mul_f32_e32 v37, v21, v55
	v_rndne_f32_e32 v34, v34
	v_cvt_i32_f32_e32 v35, v35
	v_rndne_f32_e32 v36, v36
	v_rndne_f32_e32 v37, v37
	v_cvt_i32_f32_e32 v34, v34
	v_cvt_i32_f32_sdwa v36, v36 dst_sel:WORD_1 dst_unused:UNUSED_PAD src0_sel:DWORD
	v_cvt_i32_f32_e32 v37, v37
	v_lshlrev_b32_e32 v35, 8, v35
	v_and_b32_e32 v35, 0xff00, v35
	v_and_b32_e32 v36, 0xff0000, v36
	v_perm_b32 v34, v37, v34, s68
	v_or3_b32 v34, v34, v35, v36
	v_mul_f32_e32 v36, v21, v57
	v_mul_f32_e32 v35, v21, v56
	v_rndne_f32_e32 v36, v36
	v_mul_f32_e32 v37, v21, v58
	v_mul_f32_e32 v21, v21, v59
	v_rndne_f32_e32 v35, v35
	v_cvt_i32_f32_e32 v36, v36
	v_rndne_f32_e32 v37, v37
	v_rndne_f32_e32 v21, v21
	v_cvt_i32_f32_e32 v35, v35
	v_cvt_i32_f32_sdwa v37, v37 dst_sel:WORD_1 dst_unused:UNUSED_PAD src0_sel:DWORD
	v_cvt_i32_f32_e32 v21, v21
	v_lshlrev_b32_e32 v36, 8, v36
	v_and_b32_e32 v36, 0xff00, v36
	v_and_b32_e32 v37, 0xff0000, v37
	v_perm_b32 v21, v21, v35, s68
	v_or3_b32 v35, v21, v36, v37
	v_lshl_add_u64 v[36:37], v[18:19], 0, s[12:13]
	global_store_dwordx4 v[36:37], v[28:31], off
	global_store_dwordx4 v[36:37], v[32:35], off offset:16
	s_and_saveexec_b64 s[8:9], s[4:5]
	s_cbranch_execz .LBB0_556
	v_mul_f32_e32 v28, 0x3c010204, v20
	v_mov_b64_e32 v[20:21], s[6:7]
	global_store_dword v[20:21], v28, off
.LBB0_556:
	s_or_b64 exec, exec, s[8:9]
	s_waitcnt vmcnt(2)
	v_cvt_f32_f16_e32 v20, v14
	v_cvt_f32_f16_sdwa v14, v14 dst_sel:DWORD dst_unused:UNUSED_PAD src0_sel:WORD_1
	v_cvt_f32_f16_e32 v21, v15
	v_cvt_f32_f16_sdwa v15, v15 dst_sel:DWORD dst_unused:UNUSED_PAD src0_sel:WORD_1
	v_cvt_f32_f16_e32 v28, v16
	v_cvt_f32_f16_sdwa v16, v16 dst_sel:DWORD dst_unused:UNUSED_PAD src0_sel:WORD_1
	v_cvt_f32_f16_e32 v29, v17
	v_cvt_f32_f16_sdwa v17, v17 dst_sel:DWORD dst_unused:UNUSED_PAD src0_sel:WORD_1
	v_max3_f32 v30, |v20|, 0, |v14|
	v_cvt_f32_f16_e32 v31, v10
	v_cvt_f32_f16_sdwa v10, v10 dst_sel:DWORD dst_unused:UNUSED_PAD src0_sel:WORD_1
	v_max3_f32 v30, v30, |v21|, |v15|
	v_cvt_f32_f16_e32 v32, v11
	v_cvt_f32_f16_sdwa v11, v11 dst_sel:DWORD dst_unused:UNUSED_PAD src0_sel:WORD_1
	v_max3_f32 v30, v30, |v28|, |v16|
	v_cvt_f32_f16_e32 v33, v12
	v_cvt_f32_f16_sdwa v12, v12 dst_sel:DWORD dst_unused:UNUSED_PAD src0_sel:WORD_1
	v_max3_f32 v30, v30, |v29|, |v17|
	v_cvt_f32_f16_e32 v34, v13
	v_cvt_f32_f16_sdwa v13, v13 dst_sel:DWORD dst_unused:UNUSED_PAD src0_sel:WORD_1
	v_max3_f32 v30, v30, |v31|, |v10|
	v_cvt_f32_f16_e32 v35, v6
	v_cvt_f32_f16_sdwa v36, v6 dst_sel:DWORD dst_unused:UNUSED_PAD src0_sel:WORD_1
	v_max3_f32 v30, v30, |v32|, |v11|
	v_cvt_f32_f16_e32 v37, v7
	v_cvt_f32_f16_sdwa v38, v7 dst_sel:DWORD dst_unused:UNUSED_PAD src0_sel:WORD_1
	v_max3_f32 v30, v30, |v33|, |v12|
	v_cvt_f32_f16_e32 v39, v8
	v_cvt_f32_f16_sdwa v40, v8 dst_sel:DWORD dst_unused:UNUSED_PAD src0_sel:WORD_1
	v_max3_f32 v30, v30, |v34|, |v13|
	v_cvt_f32_f16_e32 v41, v9
	v_cvt_f32_f16_sdwa v9, v9 dst_sel:DWORD dst_unused:UNUSED_PAD src0_sel:WORD_1
	v_max3_f32 v6, v30, |v35|, |v36|
	v_cvt_f32_f16_e32 v30, v2
	v_cvt_f32_f16_sdwa v42, v2 dst_sel:DWORD dst_unused:UNUSED_PAD src0_sel:WORD_1
	v_max3_f32 v6, v6, |v37|, |v38|
	v_cvt_f32_f16_e32 v43, v3
	v_cvt_f32_f16_sdwa v3, v3 dst_sel:DWORD dst_unused:UNUSED_PAD src0_sel:WORD_1
	v_max3_f32 v6, v6, |v39|, |v40|
	v_cvt_f32_f16_e32 v44, v4
	v_cvt_f32_f16_sdwa v45, v4 dst_sel:DWORD dst_unused:UNUSED_PAD src0_sel:WORD_1
	v_max3_f32 v6, v6, |v41|, |v9|
	v_cvt_f32_f16_e32 v46, v5
	v_cvt_f32_f16_sdwa v47, v5 dst_sel:DWORD dst_unused:UNUSED_PAD src0_sel:WORD_1
	v_max3_f32 v2, v6, |v30|, |v42|
	v_max3_f32 v2, v2, |v43|, |v3|
	v_max3_f32 v2, v2, |v44|, |v45|
	v_max3_f32 v2, v2, |v46|, |v47|
	ds_bpermute_b32 v4, v22, v2
	s_waitcnt lgkmcnt(0)
	v_max_f32_e32 v4, v4, v4
	v_max_f32_e32 v2, v2, v4
	ds_bpermute_b32 v4, v23, v2
	s_waitcnt lgkmcnt(0)
	v_max_f32_e32 v4, v4, v4
	v_max_f32_e32 v2, v2, v4
	ds_bpermute_b32 v4, v24, v2
	s_waitcnt lgkmcnt(0)
	v_max_f32_e32 v4, v4, v4
	v_max_f32_e32 v2, v2, v4
	ds_bpermute_b32 v4, v26, v2
	s_waitcnt lgkmcnt(0)
	v_max_f32_e32 v4, v4, v4
	v_max_f32_e32 v2, v2, v4
	ds_bpermute_b32 v4, v27, v2
	s_waitcnt lgkmcnt(0)
	v_max_f32_e32 v4, v4, v4
	v_max_f32_e32 v2, v2, v4
	ds_bpermute_b32 v4, v25, v2
	s_waitcnt lgkmcnt(0)
	v_max_f32_e32 v4, v4, v4
	v_max_f32_e32 v2, v2, v4
	v_div_scale_f32 v4, s[8:9], v2, v2, s43
	v_rcp_f32_e32 v5, v4
	s_lshl_b64 s[8:9], s[10:11], 11
	v_fma_f32 v6, -v4, v5, 1.0
	v_fmac_f32_e32 v5, v6, v5
	v_div_scale_f32 v6, vcc, s43, v2, s43
	v_mul_f32_e32 v7, v6, v5
	v_fma_f32 v8, -v4, v7, v6
	v_fmac_f32_e32 v7, v8, v5
	v_fma_f32 v4, -v4, v7, v6
	v_div_fmas_f32 v4, v4, v5, v7
	v_div_fixup_f32 v4, v4, v2, s43
	v_cmp_lt_f32_e32 vcc, 0, v2
	s_nop 1
	v_cndmask_b32_e32 v22, 0, v4, vcc
	v_mul_f32_e32 v5, v22, v14
	v_mul_f32_e32 v4, v22, v20
	v_rndne_f32_e32 v5, v5
	v_mul_f32_e32 v6, v22, v21
	v_mul_f32_e32 v7, v22, v15
	v_rndne_f32_e32 v4, v4
	v_cvt_i32_f32_e32 v5, v5
	v_rndne_f32_e32 v6, v6
	v_rndne_f32_e32 v7, v7
	v_cvt_i32_f32_e32 v4, v4
	v_cvt_i32_f32_sdwa v6, v6 dst_sel:WORD_1 dst_unused:UNUSED_PAD src0_sel:DWORD
	v_cvt_i32_f32_e32 v7, v7
	v_lshlrev_b32_e32 v5, 8, v5
	v_and_b32_e32 v5, 0xff00, v5
	v_and_b32_e32 v6, 0xff0000, v6
	v_perm_b32 v4, v7, v4, s68
	v_or3_b32 v4, v4, v5, v6
	v_mul_f32_e32 v6, v22, v16
	v_mul_f32_e32 v5, v22, v28
	v_rndne_f32_e32 v6, v6
	v_mul_f32_e32 v7, v22, v29
	v_mul_f32_e32 v8, v22, v17
	v_rndne_f32_e32 v5, v5
	v_cvt_i32_f32_e32 v6, v6
	v_rndne_f32_e32 v7, v7
	v_rndne_f32_e32 v8, v8
	v_cvt_i32_f32_e32 v5, v5
	v_cvt_i32_f32_sdwa v7, v7 dst_sel:WORD_1 dst_unused:UNUSED_PAD src0_sel:DWORD
	v_cvt_i32_f32_e32 v8, v8
	v_lshlrev_b32_e32 v6, 8, v6
	v_and_b32_e32 v6, 0xff00, v6
	v_and_b32_e32 v7, 0xff0000, v7
	v_perm_b32 v5, v8, v5, s68
	v_or3_b32 v5, v5, v6, v7
	v_mul_f32_e32 v7, v22, v10
	v_mul_f32_e32 v6, v22, v31
	v_rndne_f32_e32 v7, v7
	v_mul_f32_e32 v8, v22, v32
	v_mul_f32_e32 v10, v22, v11
	v_rndne_f32_e32 v6, v6
	v_cvt_i32_f32_e32 v7, v7
	v_rndne_f32_e32 v8, v8
	v_rndne_f32_e32 v10, v10
	v_cvt_i32_f32_e32 v6, v6
	v_cvt_i32_f32_sdwa v8, v8 dst_sel:WORD_1 dst_unused:UNUSED_PAD src0_sel:DWORD
	v_cvt_i32_f32_e32 v10, v10
	v_lshlrev_b32_e32 v7, 8, v7
	v_and_b32_e32 v7, 0xff00, v7
	v_and_b32_e32 v8, 0xff0000, v8
	v_perm_b32 v6, v10, v6, s68
	v_or3_b32 v6, v6, v7, v8
	v_mul_f32_e32 v8, v22, v12
	v_mul_f32_e32 v7, v22, v33
	v_rndne_f32_e32 v8, v8
	v_mul_f32_e32 v10, v22, v34
	v_mul_f32_e32 v11, v22, v13
	v_rndne_f32_e32 v7, v7
	v_cvt_i32_f32_e32 v8, v8
	v_rndne_f32_e32 v10, v10
	v_rndne_f32_e32 v11, v11
	v_cvt_i32_f32_e32 v7, v7
	v_cvt_i32_f32_sdwa v10, v10 dst_sel:WORD_1 dst_unused:UNUSED_PAD src0_sel:DWORD
	v_cvt_i32_f32_e32 v11, v11
	v_lshlrev_b32_e32 v8, 8, v8
	v_and_b32_e32 v8, 0xff00, v8
	v_and_b32_e32 v10, 0xff0000, v10
	v_perm_b32 v7, v11, v7, s68
	v_or3_b32 v7, v7, v8, v10
	v_mul_f32_e32 v10, v22, v36
	v_mul_f32_e32 v8, v22, v35
	v_rndne_f32_e32 v10, v10
	v_mul_f32_e32 v11, v22, v37
	v_mul_f32_e32 v12, v22, v38
	v_rndne_f32_e32 v8, v8
	v_cvt_i32_f32_e32 v10, v10
	v_rndne_f32_e32 v11, v11
	v_rndne_f32_e32 v12, v12
	v_cvt_i32_f32_e32 v8, v8
	v_cvt_i32_f32_sdwa v11, v11 dst_sel:WORD_1 dst_unused:UNUSED_PAD src0_sel:DWORD
	v_cvt_i32_f32_e32 v12, v12
	v_lshlrev_b32_e32 v10, 8, v10
	v_and_b32_e32 v10, 0xff00, v10
	v_and_b32_e32 v11, 0xff0000, v11
	v_perm_b32 v8, v12, v8, s68
	v_or3_b32 v8, v8, v10, v11
	v_mul_f32_e32 v11, v22, v40
	v_mul_f32_e32 v10, v22, v39
	v_rndne_f32_e32 v11, v11
	v_mul_f32_e32 v12, v22, v41
	v_mul_f32_e32 v9, v22, v9
	v_rndne_f32_e32 v10, v10
	v_cvt_i32_f32_e32 v11, v11
	v_rndne_f32_e32 v12, v12
	v_rndne_f32_e32 v9, v9
	v_cvt_i32_f32_e32 v10, v10
	v_cvt_i32_f32_sdwa v12, v12 dst_sel:WORD_1 dst_unused:UNUSED_PAD src0_sel:DWORD
	v_cvt_i32_f32_e32 v9, v9
	v_lshlrev_b32_e32 v11, 8, v11
	v_and_b32_e32 v11, 0xff00, v11
	v_and_b32_e32 v12, 0xff0000, v12
	v_perm_b32 v9, v9, v10, s68
	v_or3_b32 v9, v9, v11, v12
	v_mul_f32_e32 v11, v22, v42
	v_mul_f32_e32 v10, v22, v30
	v_rndne_f32_e32 v11, v11
	v_mul_f32_e32 v12, v22, v43
	v_mul_f32_e32 v3, v22, v3
	v_rndne_f32_e32 v10, v10
	v_cvt_i32_f32_e32 v11, v11
	v_rndne_f32_e32 v12, v12
	v_rndne_f32_e32 v3, v3
	v_cvt_i32_f32_e32 v10, v10
	v_cvt_i32_f32_sdwa v12, v12 dst_sel:WORD_1 dst_unused:UNUSED_PAD src0_sel:DWORD
	v_cvt_i32_f32_e32 v3, v3
	v_lshlrev_b32_e32 v11, 8, v11
	v_and_b32_e32 v11, 0xff00, v11
	v_and_b32_e32 v12, 0xff0000, v12
	v_perm_b32 v3, v3, v10, s68
	v_or3_b32 v10, v3, v11, v12
	v_mul_f32_e32 v11, v22, v45
	v_mul_f32_e32 v3, v22, v44
	v_rndne_f32_e32 v11, v11
	v_mul_f32_e32 v12, v22, v46
	v_mul_f32_e32 v13, v22, v47
	v_rndne_f32_e32 v3, v3
	v_cvt_i32_f32_e32 v11, v11
	v_rndne_f32_e32 v12, v12
	v_rndne_f32_e32 v13, v13
	v_cvt_i32_f32_e32 v3, v3
	v_cvt_i32_f32_sdwa v12, v12 dst_sel:WORD_1 dst_unused:UNUSED_PAD src0_sel:DWORD
	v_cvt_i32_f32_e32 v13, v13
	v_lshlrev_b32_e32 v11, 8, v11
	v_and_b32_e32 v11, 0xff00, v11
	v_and_b32_e32 v12, 0xff0000, v12
	v_perm_b32 v3, v13, v3, s68
	v_or3_b32 v11, v3, v11, v12
	v_lshl_add_u64 v[12:13], v[18:19], 0, s[8:9]
	global_store_dwordx4 v[12:13], v[4:7], off
	global_store_dwordx4 v[12:13], v[8:11], off offset:16
	s_and_saveexec_b64 s[8:9], s[4:5]
	s_cbranch_execz .LBB0_558
	v_mul_f32_e32 v4, 0x3c010204, v2
	v_mov_b64_e32 v[2:3], s[6:7]
	global_store_dword v[2:3], v4, off offset:1024
